# prep phase: step B weight fragments and step A shifted-v row loads requested together (batched loads); GLA c-tile s_prev loads hoisted
# speedup vs baseline: 1.0176x; 1.0002x over previous
; #define LAS __attribute__((address_space(3)))
; __device__ __forceinline__ float bflo(unsigned w) { return __uint_as_float(w << 16); }
; __device__ __forceinline__ float bfhi(unsigned w) { return __uint_as_float(w & 0xffff0000u); }
; __device__ __forceinline__ f32x4 mfma16(bf16x8 a, bf16x8 b, f32x4 c) { return __builtin_amdgcn_mfma_f32_16x16x32_bf16(a, b, c, 0, 0, 0); }
; __device__ __forceinline__ void gla_gcum(LAS unsigned char* lds, const GlaArgs& A, int t0, int h, int tid) {
;     ...
;     { const int d = tid & 63, i0 = tid >> 6; float au[16]; const float ab = A.abias[h * 64 + d];
; #pragma unroll
;       for (int j = 0; j < 16; ++j) au[j] = A.aup[j * 256 + h * 64 + d];
;       u32x4 al0[8], al1[8];
; #pragma unroll
;       for (int e = 0; e < 8; ++e) { const u32x4* ap = (const u32x4*)(A.Ug + (size_t)(t0 + i0 + 8 * e) * 1792 + 1024); al0[e] = ap[0]; al1[e] = ap[1]; }
; #pragma unroll
;       for (int e = 0; e < 8; ++e) { const int i = i0 + 8 * e; const u32x4 a0 = al0[e], a1 = al1[e];
;           float x = ab;
;           x += bflo(a0.x) * au[0] + bfhi(a0.x) * au[1] + bflo(a0.y) * au[2] + bfhi(a0.y) * au[3] + bflo(a0.z) * au[4] + bfhi(a0.z) * au[5] + bflo(a0.w) * au[6] + bfhi(a0.w) * au[7];
;           x += bflo(a1.x) * au[8] + bfhi(a1.x) * au[9] + bflo(a1.y) * au[10] + bfhi(a1.y) * au[11] + bflo(a1.z) * au[12] + bfhi(a1.z) * au[13] + bflo(a1.w) * au[14] + bfhi(a1.w) * au[15];
;           const float ls = fminf(x, 0.f) - __logf(1.f + __expf(-fabsf(x)));
;           GC[i * 65 + d] = ls * (1.0f / 16.0f); } }
; __device__ __forceinline__ void gla_c_tile(LAS unsigned char* lds, const GlaArgs& A, int tile, int tid) {
;     ...
;     const bf16_t* sp = A.spT + ((size_t)bh * 64 + n) * 128 * 64;
; #pragma unroll
;     for (int ks = 0; ks < 2; ++ks) { const int ko = ks * 32 + fq * 8; const bf16x8 a1 = *(LAS const bf16x8*)(AL + (16 * mt + fr) * 72 + ko), a2 = *(LAS const bf16x8*)(QG + (16 * mt + fr) * 72 + ko);
; #pragma unroll
;         for (int q = 0; q < 4; ++q) { const int nt = (wave & 1) * 4 + q;
;             acc[q] = mfma16(*(LAS const bf16x8*)(VT + (16 * nt + fr) * 72 + ko), a1, acc[q]);
;             acc[q] = mfma16(*(const bf16x8*)(sp + (size_t)(16 * nt + fr) * 64 + ko), a2, acc[q]); } }
.LBB0_310:
	s_mov_b32 s36, 0x18100000
	s_mov_b32 s37, 0
	v_lshl_add_u64 v[228:229], v[96:97], 0, s[52:53]
	v_lshl_add_u64 v[228:229], v[228:229], 0, s[36:37]
	global_load_dwordx4 v[176:179], v[228:229], off
	global_load_dwordx4 v[192:195], v[228:229], off offset:64
	v_lshl_add_u64 v[228:229], v[94:95], 0, s[52:53]
	v_lshl_add_u64 v[228:229], v[228:229], 0, s[36:37]
	global_load_dwordx4 v[180:183], v[228:229], off
	global_load_dwordx4 v[196:199], v[228:229], off offset:64
	v_lshl_add_u64 v[228:229], v[92:93], 0, s[52:53]
	v_lshl_add_u64 v[228:229], v[228:229], 0, s[36:37]
	global_load_dwordx4 v[184:187], v[228:229], off
	global_load_dwordx4 v[200:203], v[228:229], off offset:64
	v_lshl_add_u64 v[228:229], v[90:91], 0, s[52:53]
	v_lshl_add_u64 v[228:229], v[228:229], 0, s[36:37]
	global_load_dwordx4 v[188:191], v[228:229], off
	global_load_dwordx4 v[204:207], v[228:229], off offset:64
	v_add_u32_e32 v155, s62, v144
	v_mov_b64_e32 v[2:3], s[54:55]
	v_mad_i64_i32 v[4:5], s[38:39], v155, s80, v[2:3]
	global_load_dwordx4 v[10:13], v[4:5], off offset:2048
	global_load_dwordx4 v[14:17], v[4:5], off offset:2064
	global_load_dword v161, v[60:61], off offset:1024
	global_load_dword v160, v[60:61], off offset:2048
	global_load_dword v159, v[60:61], off offset:3072
	global_load_dword v122, v[62:63], off
	global_load_dword v121, v[64:65], off
	global_load_dword v120, v[66:67], off
	global_load_dword v119, v[68:69], off
	global_load_dword v163, v[60:61], off
	global_load_dword v118, v[72:73], off
	global_load_dword v117, v[74:75], off
	global_load_dword v116, v[76:77], off
	global_load_dword v115, v[78:79], off
	global_load_dword v114, v[80:81], off
	global_load_dword v113, v[82:83], off
	global_load_dword v112, v[84:85], off
	global_load_dword v123, v[70:71], off
	global_load_dword v162, v[58:59], off
	v_add_u32_e32 v111, 8, v155
	v_mad_i64_i32 v[4:5], s[38:39], v111, s80, v[2:3]
	global_load_dwordx4 v[50:53], v[4:5], off offset:2048
	global_load_dwordx4 v[54:57], v[4:5], off offset:2064
	v_add_u32_e32 v110, 16, v155
	v_add_u32_e32 v109, 24, v155
	v_add_u32_e32 v108, 32, v155
	v_add_u32_e32 v158, 40, v155
	v_add_u32_e32 v157, 48, v155
	v_add_u32_e32 v156, 56, v155
	v_mad_i64_i32 v[6:7], s[38:39], v110, s80, v[2:3]
	v_mad_i64_i32 v[8:9], s[38:39], v109, s80, v[2:3]
	v_mad_i64_i32 v[18:19], s[38:39], v108, s80, v[2:3]
	v_mad_i64_i32 v[22:23], s[38:39], v158, s80, v[2:3]
	v_mad_i64_i32 v[164:165], s[38:39], v157, s80, v[2:3]
	v_mad_i64_i32 v[166:167], s[38:39], v156, s80, v[2:3]
	global_load_dwordx4 v[42:45], v[6:7], off offset:2064
	global_load_dwordx4 v[46:49], v[6:7], off offset:2048
	global_load_dwordx4 v[34:37], v[8:9], off offset:2064
	global_load_dwordx4 v[38:41], v[8:9], off offset:2048
	global_load_dwordx4 v[26:29], v[18:19], off offset:2064
	global_load_dwordx4 v[30:33], v[18:19], off offset:2048
	s_nop 0
	global_load_dwordx4 v[18:21], v[22:23], off offset:2064
	s_nop 0
	global_load_dwordx4 v[22:25], v[22:23], off offset:2048
	s_nop 0
	global_load_dwordx4 v[2:5], v[164:165], off offset:2064
	global_load_dwordx4 v[6:9], v[164:165], off offset:2048
	s_movk_i32 s36, 0xffef
	s_waitcnt vmcnt(30)
	v_lshlrev_b32_e32 v164, 16, v10
	v_and_b32_e32 v10, 0xffff0000, v10
	s_waitcnt vmcnt(29)
	v_lshlrev_b32_e32 v170, 16, v14
	v_and_b32_e32 v14, 0xffff0000, v14
	s_waitcnt vmcnt(28)
	v_mul_f32_e32 v10, v161, v10
	v_lshlrev_b32_e32 v165, 16, v11
	v_and_b32_e32 v11, 0xffff0000, v11
	v_lshlrev_b32_e32 v171, 16, v15
	v_lshlrev_b32_e32 v168, 16, v12
	s_waitcnt vmcnt(21)
	v_fmac_f32_e32 v10, v163, v164
	s_waitcnt vmcnt(20)
	v_mul_f32_e32 v14, v118, v14
	v_fmac_f32_e32 v10, v160, v165
	v_and_b32_e32 v15, 0xffff0000, v15
	v_fmac_f32_e32 v10, v159, v11
	v_and_b32_e32 v12, 0xffff0000, v12
	v_lshlrev_b32_e32 v172, 16, v16
	v_fmac_f32_e32 v10, v122, v168
	s_waitcnt vmcnt(13)
	v_fmac_f32_e32 v14, v123, v170
	v_fmac_f32_e32 v14, v117, v171
	v_fmac_f32_e32 v14, v116, v15
	v_lshlrev_b32_e32 v169, 16, v13
	v_and_b32_e32 v16, 0xffff0000, v16
	v_fmac_f32_e32 v14, v115, v172
	v_fmac_f32_e32 v10, v121, v12
	v_and_b32_e32 v13, 0xffff0000, v13
	v_lshlrev_b32_e32 v173, 16, v17
	v_fmac_f32_e32 v14, v114, v16
	v_fmac_f32_e32 v10, v120, v169
	v_and_b32_e32 v17, 0xffff0000, v17
	v_fmac_f32_e32 v14, v113, v173
	v_fmac_f32_e32 v10, v119, v13
	v_fmac_f32_e32 v14, v112, v17
	s_waitcnt vmcnt(12)
	v_add_f32_e32 v10, v162, v10
	v_add_f32_e32 v164, v10, v14
	v_mul_f32_e64 v10, |v164|, s77
	v_exp_f32_e32 v165, v10
	global_load_dwordx4 v[10:13], v[166:167], off offset:2064
	global_load_dwordx4 v[14:17], v[166:167], off offset:2048
	s_waitcnt vmcnt(13)
	v_lshlrev_b32_e32 v166, 16, v50
	v_and_b32_e32 v50, 0xffff0000, v50
	v_mul_f32_e32 v50, v161, v50
	v_fmac_f32_e32 v50, v163, v166
	v_lshlrev_b32_e32 v166, 16, v51
	v_fmac_f32_e32 v50, v160, v166
	v_and_b32_e32 v51, 0xffff0000, v51
	v_fmac_f32_e32 v50, v159, v51
	v_lshlrev_b32_e32 v51, 16, v52
	v_fmac_f32_e32 v50, v122, v51
	v_and_b32_e32 v51, 0xffff0000, v52
	v_fmac_f32_e32 v50, v121, v51
	v_lshlrev_b32_e32 v51, 16, v53
	v_fmac_f32_e32 v50, v120, v51
	v_and_b32_e32 v51, 0xffff0000, v53
	s_waitcnt vmcnt(12)
; __device__ __forceinline__ float bflo(unsigned w) { return __uint_as_float(w << 16); }
; __device__ __forceinline__ float bfhi(unsigned w) { return __uint_as_float(w & 0xffff0000u); }
; __device__ __forceinline__ void gla_gcum(LAS unsigned char* lds, const GlaArgs& A, int t0, int h, int tid) {
;     ...
;       for (int e = 0; e < 8; ++e) { const int i = i0 + 8 * e; const u32x4 a0 = al0[e], a1 = al1[e];
;           float x = ab;
;           x += bflo(a0.x) * au[0] + bfhi(a0.x) * au[1] + bflo(a0.y) * au[2] + bfhi(a0.y) * au[3] + bflo(a0.z) * au[4] + bfhi(a0.z) * au[5] + bflo(a0.w) * au[6] + bfhi(a0.w) * au[7];
;           x += bflo(a1.x) * au[8] + bfhi(a1.x) * au[9] + bflo(a1.y) * au[10] + bfhi(a1.y) * au[11] + bflo(a1.z) * au[12] + bfhi(a1.z) * au[13] + bflo(a1.w) * au[14] + bfhi(a1.w) * au[15];
;           const float ls = fminf(x, 0.f) - __logf(1.f + __expf(-fabsf(x)));
;           GC[i * 65 + d] = ls * (1.0f / 16.0f); } }
	v_and_b32_e32 v52, 0xffff0000, v54
	v_fmac_f32_e32 v50, v119, v51
	v_lshlrev_b32_e32 v51, 16, v54
	v_mul_f32_e32 v52, v118, v52
	v_fmac_f32_e32 v52, v123, v51
	v_lshlrev_b32_e32 v51, 16, v55
	v_fmac_f32_e32 v52, v117, v51
	v_and_b32_e32 v51, 0xffff0000, v55
	v_add_f32_e32 v165, 1.0, v165
	v_fmac_f32_e32 v52, v116, v51
	v_lshlrev_b32_e32 v51, 16, v56
	v_cmp_gt_f32_e32 vcc, s76, v165
	v_fmac_f32_e32 v52, v115, v51
	v_and_b32_e32 v51, 0xffff0000, v56
	v_cndmask_b32_e64 v167, 0, 32, vcc
	v_fmac_f32_e32 v52, v114, v51
	v_lshlrev_b32_e32 v51, 16, v57
	v_ldexp_f32 v165, v165, v167
	v_fmac_f32_e32 v52, v113, v51
	v_and_b32_e32 v51, 0xffff0000, v57
	v_log_f32_e32 v165, v165
	v_add_f32_e32 v50, v162, v50
	v_fmac_f32_e32 v52, v112, v51
	v_add_f32_e32 v50, v50, v52
	v_mul_f32_e64 v51, |v50|, s77
	v_exp_f32_e32 v51, v51
	v_mul_f32_e32 v168, 0x3f317217, v165
	v_fma_f32 v168, v165, s81, -v168
	v_fmac_f32_e32 v168, 0x3377d1cf, v165
	v_cndmask_b32_e32 v167, 0, v238, vcc
	v_fmac_f32_e32 v168, 0x3f317217, v165
	v_cmp_lt_f32_e64 vcc, |v165|, s82
	v_add_f32_e32 v51, 1.0, v51
	v_min_f32_e32 v164, 0, v164
	v_cndmask_b32_e32 v165, v165, v168, vcc
	v_cmp_gt_f32_e32 vcc, s76, v51
	v_sub_f32_e32 v52, v165, v167
	v_sub_f32_e32 v52, v164, v52
	v_cndmask_b32_e64 v53, 0, 32, vcc
	v_ldexp_f32 v51, v51, v53
	v_log_f32_e32 v51, v51
	v_mul_f32_e32 v52, 0x3d800000, v52
	v_add_u32_e32 v53, v132, v133
	ds_write_b32 v53, v52
	v_mul_f32_e32 v52, 0x3f317217, v51
	v_fma_f32 v52, v51, s81, -v52
	v_fmac_f32_e32 v52, 0x3377d1cf, v51
	v_fmac_f32_e32 v52, 0x3f317217, v51
	v_cmp_lt_f32_e64 s[38:39], |v51|, s82
	v_min_f32_e32 v50, 0, v50
	s_nop 0
	v_cndmask_b32_e64 v51, v51, v52, s[38:39]
	s_waitcnt vmcnt(10)
	v_lshlrev_b32_e32 v52, 16, v46
	v_and_b32_e32 v46, 0xffff0000, v46
	v_mul_f32_e32 v46, v161, v46
	v_fmac_f32_e32 v46, v163, v52
	v_lshlrev_b32_e32 v52, 16, v47
	v_fmac_f32_e32 v46, v160, v52
	v_and_b32_e32 v47, 0xffff0000, v47
	v_fmac_f32_e32 v46, v159, v47
	v_lshlrev_b32_e32 v47, 16, v48
	v_fmac_f32_e32 v46, v122, v47
	v_and_b32_e32 v47, 0xffff0000, v48
	v_fmac_f32_e32 v46, v121, v47
	v_lshlrev_b32_e32 v47, 16, v49
	v_fmac_f32_e32 v46, v120, v47
	v_and_b32_e32 v47, 0xffff0000, v49
	v_fmac_f32_e32 v46, v119, v47
	v_lshlrev_b32_e32 v47, 16, v42
	v_and_b32_e32 v42, 0xffff0000, v42
	v_mul_f32_e32 v42, v118, v42
	v_fmac_f32_e32 v42, v123, v47
	v_lshlrev_b32_e32 v47, 16, v43
	v_fmac_f32_e32 v42, v117, v47
	v_and_b32_e32 v43, 0xffff0000, v43
	v_fmac_f32_e32 v42, v116, v43
	v_lshlrev_b32_e32 v43, 16, v44
	v_fmac_f32_e32 v42, v115, v43
	v_and_b32_e32 v43, 0xffff0000, v44
	v_fmac_f32_e32 v42, v114, v43
	v_lshlrev_b32_e32 v43, 16, v45
	v_fmac_f32_e32 v42, v113, v43
	v_and_b32_e32 v43, 0xffff0000, v45
	v_add_f32_e32 v46, v162, v46
	v_fmac_f32_e32 v42, v112, v43
	v_add_f32_e32 v42, v46, v42
	v_mul_f32_e64 v43, |v42|, s77
	v_exp_f32_e32 v43, v43
	v_cndmask_b32_e32 v44, 0, v238, vcc
	v_sub_f32_e32 v44, v51, v44
	v_sub_f32_e32 v44, v50, v44
	v_add_f32_e32 v43, 1.0, v43
	v_cmp_gt_f32_e32 vcc, s76, v43
	v_mul_f32_e32 v44, 0x3d800000, v44
	ds_write_b32 v53, v44 offset:2080
	v_cndmask_b32_e64 v45, 0, 32, vcc
	v_ldexp_f32 v43, v43, v45
	v_log_f32_e32 v43, v43
	v_min_f32_e32 v42, 0, v42
	v_mul_f32_e32 v44, 0x3f317217, v43
	v_fma_f32 v44, v43, s81, -v44
	v_fmac_f32_e32 v44, 0x3377d1cf, v43
	v_fmac_f32_e32 v44, 0x3f317217, v43
	v_cmp_lt_f32_e64 s[38:39], |v43|, s82
	s_nop 1
	v_cndmask_b32_e64 v43, v43, v44, s[38:39]
	s_waitcnt vmcnt(8)
	v_lshlrev_b32_e32 v44, 16, v38
	v_and_b32_e32 v38, 0xffff0000, v38
	v_mul_f32_e32 v38, v161, v38
	v_fmac_f32_e32 v38, v163, v44
	v_lshlrev_b32_e32 v44, 16, v39
	v_fmac_f32_e32 v38, v160, v44
	v_and_b32_e32 v39, 0xffff0000, v39
	v_fmac_f32_e32 v38, v159, v39
	v_lshlrev_b32_e32 v39, 16, v40
	v_fmac_f32_e32 v38, v122, v39
	v_and_b32_e32 v39, 0xffff0000, v40
	v_fmac_f32_e32 v38, v121, v39
	v_lshlrev_b32_e32 v39, 16, v41
	v_fmac_f32_e32 v38, v120, v39
	v_and_b32_e32 v39, 0xffff0000, v41
	v_fmac_f32_e32 v38, v119, v39
	v_lshlrev_b32_e32 v39, 16, v34
	v_and_b32_e32 v34, 0xffff0000, v34
	v_mul_f32_e32 v34, v118, v34
	v_fmac_f32_e32 v34, v123, v39
	v_lshlrev_b32_e32 v39, 16, v35
	v_fmac_f32_e32 v34, v117, v39
	v_and_b32_e32 v35, 0xffff0000, v35
	v_fmac_f32_e32 v34, v116, v35
	v_lshlrev_b32_e32 v35, 16, v36
	v_fmac_f32_e32 v34, v115, v35
	v_and_b32_e32 v35, 0xffff0000, v36
	v_fmac_f32_e32 v34, v114, v35
	v_lshlrev_b32_e32 v35, 16, v37
	v_fmac_f32_e32 v34, v113, v35
	v_and_b32_e32 v35, 0xffff0000, v37
	v_add_f32_e32 v38, v162, v38
	v_fmac_f32_e32 v34, v112, v35
	v_add_f32_e32 v34, v38, v34
	v_mul_f32_e64 v35, |v34|, s77
	v_exp_f32_e32 v35, v35
	v_cndmask_b32_e32 v36, 0, v238, vcc
	v_sub_f32_e32 v36, v43, v36
	v_sub_f32_e32 v36, v42, v36
	v_add_f32_e32 v35, 1.0, v35
	v_cmp_gt_f32_e32 vcc, s76, v35
	v_mul_f32_e32 v36, 0x3d800000, v36
	ds_write_b32 v53, v36 offset:4160
	v_cndmask_b32_e64 v37, 0, 32, vcc
	v_ldexp_f32 v35, v35, v37
	v_log_f32_e32 v35, v35
	v_min_f32_e32 v34, 0, v34
	v_add_u32_e32 v44, 47, v155
	v_mul_f32_e32 v36, 0x3f317217, v35
	v_fma_f32 v36, v35, s81, -v36
	v_fmac_f32_e32 v36, 0x3377d1cf, v35
	v_fmac_f32_e32 v36, 0x3f317217, v35
	v_cmp_lt_f32_e64 s[38:39], |v35|, s82
	s_nop 1
	v_cndmask_b32_e64 v35, v35, v36, s[38:39]
	s_waitcnt vmcnt(6)
; __device__ __forceinline__ float bflo(unsigned w) { return __uint_as_float(w << 16); }
; __device__ __forceinline__ float bfhi(unsigned w) { return __uint_as_float(w & 0xffff0000u); }
; __device__ __forceinline__ void gla_gcum(LAS unsigned char* lds, const GlaArgs& A, int t0, int h, int tid) {
;     ...
;       for (int e = 0; e < 8; ++e) { const int i = i0 + 8 * e; const u32x4 a0 = al0[e], a1 = al1[e];
;           float x = ab;
;           x += bflo(a0.x) * au[0] + bfhi(a0.x) * au[1] + bflo(a0.y) * au[2] + bfhi(a0.y) * au[3] + bflo(a0.z) * au[4] + bfhi(a0.z) * au[5] + bflo(a0.w) * au[6] + bfhi(a0.w) * au[7];
;           x += bflo(a1.x) * au[8] + bfhi(a1.x) * au[9] + bflo(a1.y) * au[10] + bfhi(a1.y) * au[11] + bflo(a1.z) * au[12] + bfhi(a1.z) * au[13] + bflo(a1.w) * au[14] + bfhi(a1.w) * au[15];
;           const float ls = fminf(x, 0.f) - __logf(1.f + __expf(-fabsf(x)));
;           GC[i * 65 + d] = ls * (1.0f / 16.0f); } }
	v_lshlrev_b32_e32 v36, 16, v30
	v_and_b32_e32 v30, 0xffff0000, v30
	v_mul_f32_e32 v30, v161, v30
	v_fmac_f32_e32 v30, v163, v36
	v_lshlrev_b32_e32 v36, 16, v31
	v_fmac_f32_e32 v30, v160, v36
	v_and_b32_e32 v31, 0xffff0000, v31
	v_fmac_f32_e32 v30, v159, v31
	v_lshlrev_b32_e32 v31, 16, v32
	v_fmac_f32_e32 v30, v122, v31
	v_and_b32_e32 v31, 0xffff0000, v32
	v_fmac_f32_e32 v30, v121, v31
	v_lshlrev_b32_e32 v31, 16, v33
	v_fmac_f32_e32 v30, v120, v31
	v_and_b32_e32 v31, 0xffff0000, v33
	v_fmac_f32_e32 v30, v119, v31
	v_lshlrev_b32_e32 v31, 16, v26
	v_and_b32_e32 v26, 0xffff0000, v26
	v_mul_f32_e32 v26, v118, v26
	v_fmac_f32_e32 v26, v123, v31
	v_lshlrev_b32_e32 v31, 16, v27
	v_fmac_f32_e32 v26, v117, v31
	v_and_b32_e32 v27, 0xffff0000, v27
	v_fmac_f32_e32 v26, v116, v27
	v_lshlrev_b32_e32 v27, 16, v28
	v_fmac_f32_e32 v26, v115, v27
	v_and_b32_e32 v27, 0xffff0000, v28
	v_fmac_f32_e32 v26, v114, v27
	v_lshlrev_b32_e32 v27, 16, v29
	v_fmac_f32_e32 v26, v113, v27
	v_and_b32_e32 v27, 0xffff0000, v29
	v_add_f32_e32 v30, v162, v30
	v_fmac_f32_e32 v26, v112, v27
	v_add_f32_e32 v26, v30, v26
	v_mul_f32_e64 v27, |v26|, s77
	v_exp_f32_e32 v27, v27
	v_cndmask_b32_e32 v28, 0, v238, vcc
	v_sub_f32_e32 v28, v35, v28
	v_sub_f32_e32 v28, v34, v28
	v_add_f32_e32 v27, 1.0, v27
	v_cmp_gt_f32_e32 vcc, s76, v27
	v_mul_f32_e32 v28, 0x3d800000, v28
	ds_write_b32 v53, v28 offset:6240
	v_cndmask_b32_e64 v29, 0, 32, vcc
	v_ldexp_f32 v27, v27, v29
	v_log_f32_e32 v27, v27
	v_min_f32_e32 v26, 0, v26
	v_mul_f32_e32 v28, 0x3f317217, v27
	v_fma_f32 v28, v27, s81, -v28
	v_fmac_f32_e32 v28, 0x3377d1cf, v27
	v_fmac_f32_e32 v28, 0x3f317217, v27
	v_cmp_lt_f32_e64 s[38:39], |v27|, s82
	s_nop 1
	v_cndmask_b32_e64 v27, v27, v28, s[38:39]
	s_waitcnt vmcnt(4)
	v_lshlrev_b32_e32 v28, 16, v22
	v_and_b32_e32 v22, 0xffff0000, v22
	v_mul_f32_e32 v22, v161, v22
	v_fmac_f32_e32 v22, v163, v28
	v_lshlrev_b32_e32 v28, 16, v23
	v_fmac_f32_e32 v22, v160, v28
	v_and_b32_e32 v23, 0xffff0000, v23
	v_fmac_f32_e32 v22, v159, v23
	v_lshlrev_b32_e32 v23, 16, v24
	v_fmac_f32_e32 v22, v122, v23
	v_and_b32_e32 v23, 0xffff0000, v24
	v_fmac_f32_e32 v22, v121, v23
	v_lshlrev_b32_e32 v23, 16, v25
	v_fmac_f32_e32 v22, v120, v23
	v_and_b32_e32 v23, 0xffff0000, v25
	v_fmac_f32_e32 v22, v119, v23
	v_lshlrev_b32_e32 v23, 16, v18
	v_and_b32_e32 v18, 0xffff0000, v18
	v_mul_f32_e32 v18, v118, v18
	v_fmac_f32_e32 v18, v123, v23
	v_lshlrev_b32_e32 v23, 16, v19
	v_fmac_f32_e32 v18, v117, v23
	v_and_b32_e32 v19, 0xffff0000, v19
	v_fmac_f32_e32 v18, v116, v19
	v_lshlrev_b32_e32 v19, 16, v20
	v_fmac_f32_e32 v18, v115, v19
	v_and_b32_e32 v19, 0xffff0000, v20
	v_fmac_f32_e32 v18, v114, v19
	v_lshlrev_b32_e32 v19, 16, v21
	v_fmac_f32_e32 v18, v113, v19
	v_and_b32_e32 v19, 0xffff0000, v21
	v_add_f32_e32 v22, v162, v22
	v_fmac_f32_e32 v18, v112, v19
	v_add_f32_e32 v18, v22, v18
	v_mul_f32_e64 v19, |v18|, s77
	v_exp_f32_e32 v19, v19
	v_cndmask_b32_e32 v20, 0, v238, vcc
	v_sub_f32_e32 v20, v27, v20
	v_sub_f32_e32 v20, v26, v20
	v_add_f32_e32 v19, 1.0, v19
	v_cmp_gt_f32_e32 vcc, s76, v19
	v_mul_f32_e32 v20, 0x3d800000, v20
	ds_write_b32 v53, v20 offset:8320
	v_cndmask_b32_e64 v21, 0, 32, vcc
	v_ldexp_f32 v19, v19, v21
	v_log_f32_e32 v19, v19
	v_min_f32_e32 v18, 0, v18
	v_add_u32_e32 v22, -1, v155
	v_mul_f32_e32 v20, 0x3f317217, v19
	v_fma_f32 v20, v19, s81, -v20
	v_fmac_f32_e32 v20, 0x3377d1cf, v19
	v_fmac_f32_e32 v20, 0x3f317217, v19
	v_cmp_lt_f32_e64 s[38:39], |v19|, s82
	s_nop 1
	v_cndmask_b32_e64 v19, v19, v20, s[38:39]
	s_waitcnt vmcnt(2)
	v_lshlrev_b32_e32 v20, 16, v6
	v_and_b32_e32 v6, 0xffff0000, v6
	v_mul_f32_e32 v6, v161, v6
	v_fmac_f32_e32 v6, v163, v20
	v_lshlrev_b32_e32 v20, 16, v7
	v_fmac_f32_e32 v6, v160, v20
	v_and_b32_e32 v7, 0xffff0000, v7
	v_fmac_f32_e32 v6, v159, v7
	v_lshlrev_b32_e32 v7, 16, v8
	v_fmac_f32_e32 v6, v122, v7
	v_and_b32_e32 v7, 0xffff0000, v8
	v_fmac_f32_e32 v6, v121, v7
	v_lshlrev_b32_e32 v7, 16, v9
	v_fmac_f32_e32 v6, v120, v7
	v_and_b32_e32 v7, 0xffff0000, v9
	v_fmac_f32_e32 v6, v119, v7
	v_lshlrev_b32_e32 v7, 16, v2
	v_and_b32_e32 v2, 0xffff0000, v2
	v_mul_f32_e32 v2, v118, v2
	v_fmac_f32_e32 v2, v123, v7
	v_lshlrev_b32_e32 v7, 16, v3
	v_fmac_f32_e32 v2, v117, v7
	v_and_b32_e32 v3, 0xffff0000, v3
	v_fmac_f32_e32 v2, v116, v3
	v_lshlrev_b32_e32 v3, 16, v4
	v_fmac_f32_e32 v2, v115, v3
	v_and_b32_e32 v3, 0xffff0000, v4
	v_fmac_f32_e32 v2, v114, v3
	v_lshlrev_b32_e32 v3, 16, v5
	v_fmac_f32_e32 v2, v113, v3
	v_and_b32_e32 v3, 0xffff0000, v5
	v_add_f32_e32 v6, v162, v6
	v_fmac_f32_e32 v2, v112, v3
	v_add_f32_e32 v2, v6, v2
	v_mul_f32_e64 v3, |v2|, s77
	v_exp_f32_e32 v3, v3
	v_cndmask_b32_e32 v4, 0, v238, vcc
	v_sub_f32_e32 v4, v19, v4
	v_sub_f32_e32 v4, v18, v4
	v_add_f32_e32 v3, 1.0, v3
	v_cmp_gt_f32_e32 vcc, s76, v3
	v_mul_f32_e32 v4, 0x3d800000, v4
	ds_write_b32 v53, v4 offset:10400
	v_cndmask_b32_e64 v5, 0, 32, vcc
	v_ldexp_f32 v3, v3, v5
	v_log_f32_e32 v3, v3
	s_waitcnt vmcnt(0)
; __device__ __forceinline__ float bflo(unsigned w) { return __uint_as_float(w << 16); }
; __device__ __forceinline__ float bfhi(unsigned w) { return __uint_as_float(w & 0xffff0000u); }
; __device__ __forceinline__ void gla_gcum(LAS unsigned char* lds, const GlaArgs& A, int t0, int h, int tid) {
;     ...
;       for (int e = 0; e < 8; ++e) { const int i = i0 + 8 * e; const u32x4 a0 = al0[e], a1 = al1[e];
;           float x = ab;
;           x += bflo(a0.x) * au[0] + bfhi(a0.x) * au[1] + bflo(a0.y) * au[2] + bfhi(a0.y) * au[3] + bflo(a0.z) * au[4] + bfhi(a0.z) * au[5] + bflo(a0.w) * au[6] + bfhi(a0.w) * au[7];
;           x += bflo(a1.x) * au[8] + bfhi(a1.x) * au[9] + bflo(a1.y) * au[10] + bfhi(a1.y) * au[11] + bflo(a1.z) * au[12] + bfhi(a1.z) * au[13] + bflo(a1.w) * au[14] + bfhi(a1.w) * au[15];
;           const float ls = fminf(x, 0.f) - __logf(1.f + __expf(-fabsf(x)));
;           GC[i * 65 + d] = ls * (1.0f / 16.0f); } }
;     __syncthreads();
;     { const int lane = tid & 63, wave = tid >> 6;
; #pragma unroll
;       for (int dd = 0; dd < 8; ++dd) { const int d = wave * 8 + dd; float x = GC[lane * 65 + d];
; #pragma unroll
;           for (int o = 1; o < 64; o <<= 1) { const float y = __shfl_up(x, o); if (lane >= o) x += y; }
;           GC[lane * 65 + d] = x; } }
	v_and_b32_e32 v5, 0xffff0000, v14
	v_mul_f32_e32 v5, v161, v5
	v_and_b32_e32 v6, 0xffff0000, v10
	v_mul_f32_e32 v4, 0x3f317217, v3
	v_fma_f32 v4, v3, s81, -v4
	v_fmac_f32_e32 v4, 0x3377d1cf, v3
	v_fmac_f32_e32 v4, 0x3f317217, v3
	v_cmp_lt_f32_e64 s[38:39], |v3|, s82
	v_mul_f32_e32 v6, v118, v6
	v_min_f32_e32 v2, 0, v2
	v_cndmask_b32_e64 v3, v3, v4, s[38:39]
	v_lshlrev_b32_e32 v4, 16, v14
	v_fmac_f32_e32 v5, v163, v4
	v_lshlrev_b32_e32 v4, 16, v15
	v_fmac_f32_e32 v5, v160, v4
	v_and_b32_e32 v4, 0xffff0000, v15
	v_fmac_f32_e32 v5, v159, v4
	v_lshlrev_b32_e32 v4, 16, v16
	v_fmac_f32_e32 v5, v122, v4
	v_and_b32_e32 v4, 0xffff0000, v16
	v_fmac_f32_e32 v5, v121, v4
	v_lshlrev_b32_e32 v4, 16, v17
	v_fmac_f32_e32 v5, v120, v4
	v_and_b32_e32 v4, 0xffff0000, v17
	v_fmac_f32_e32 v5, v119, v4
	v_add_f32_e32 v4, v162, v5
	v_lshlrev_b32_e32 v5, 16, v10
	v_fmac_f32_e32 v6, v123, v5
	v_lshlrev_b32_e32 v5, 16, v11
	v_fmac_f32_e32 v6, v117, v5
	v_and_b32_e32 v5, 0xffff0000, v11
	v_fmac_f32_e32 v6, v116, v5
	v_lshlrev_b32_e32 v5, 16, v12
	v_fmac_f32_e32 v6, v115, v5
	v_and_b32_e32 v5, 0xffff0000, v12
	v_fmac_f32_e32 v6, v114, v5
	v_lshlrev_b32_e32 v5, 16, v13
	v_fmac_f32_e32 v6, v113, v5
	v_and_b32_e32 v5, 0xffff0000, v13
	v_fmac_f32_e32 v6, v112, v5
	v_add_f32_e32 v4, v4, v6
	v_mul_f32_e64 v5, |v4|, s77
	v_exp_f32_e32 v5, v5
	v_cndmask_b32_e32 v6, 0, v238, vcc
	v_sub_f32_e32 v3, v3, v6
	v_sub_f32_e32 v2, v2, v3
	v_add_f32_e32 v3, 1.0, v5
	v_cmp_gt_f32_e32 vcc, s76, v3
	v_mul_f32_e32 v2, 0x3d800000, v2
	ds_write_b32 v53, v2 offset:12480
	v_cndmask_b32_e64 v5, 0, 32, vcc
	v_ldexp_f32 v3, v3, v5
	v_log_f32_e32 v3, v3
	v_min_f32_e32 v2, 0, v4
	v_add_u32_e32 v159, s62, v134
	v_add_u32_e32 v18, -3, v155
	v_mul_f32_e32 v4, 0x3f317217, v3
	v_fma_f32 v4, v3, s81, -v4
	v_fmac_f32_e32 v4, 0x3377d1cf, v3
	v_fmac_f32_e32 v4, 0x3f317217, v3
	v_cmp_lt_f32_e64 s[38:39], |v3|, s82
	v_add_u32_e32 v20, -2, v155
	v_add_u32_e32 v26, 32, v159
	v_cndmask_b32_e64 v3, v3, v4, s[38:39]
	v_cndmask_b32_e32 v4, 0, v238, vcc
	v_sub_f32_e32 v3, v3, v4
	v_sub_f32_e32 v2, v2, v3
	v_mul_f32_e32 v2, 0x3d800000, v2
	ds_write_b32 v53, v2 offset:14560
	s_waitcnt lgkmcnt(0)
	s_barrier
	ds_read2_b32 v[2:3], v145 offset1:1
	ds_read2_b32 v[4:5], v145 offset0:6 offset1:7
	ds_read2_b32 v[6:7], v145 offset0:2 offset1:3
	ds_read2_b32 v[12:13], v145 offset0:4 offset1:5
	s_add_i32 s38, s97, s62
	s_waitcnt lgkmcnt(3)
	ds_bpermute_b32 v8, v126, v2
	ds_bpermute_b32 v9, v126, v3
	s_waitcnt lgkmcnt(3)
	ds_bpermute_b32 v10, v126, v6
	ds_bpermute_b32 v11, v126, v7
	s_waitcnt lgkmcnt(4)
	ds_bpermute_b32 v14, v126, v12
	ds_bpermute_b32 v15, v126, v13
	ds_bpermute_b32 v16, v126, v4
	ds_bpermute_b32 v17, v126, v5
	s_waitcnt lgkmcnt(4)
	v_pk_add_f32 v[10:11], v[6:7], v[10:11]
	v_pk_add_f32 v[8:9], v[2:3], v[8:9]
	v_cndmask_b32_e64 v7, v11, v7, s[4:5]
	v_cndmask_b32_e64 v6, v10, v6, s[4:5]
	ds_bpermute_b32 v10, v127, v6
	ds_bpermute_b32 v11, v127, v7
	v_cndmask_b32_e64 v3, v9, v3, s[4:5]
	v_cndmask_b32_e64 v2, v8, v2, s[4:5]
	ds_bpermute_b32 v8, v127, v2
	ds_bpermute_b32 v9, v127, v3
	s_waitcnt lgkmcnt(2)
	v_pk_add_f32 v[10:11], v[6:7], v[10:11]
	v_mov_b32_e32 v170, s38
	v_cndmask_b32_e64 v7, v11, v7, s[6:7]
	v_cndmask_b32_e64 v6, v10, v6, s[6:7]
	ds_bpermute_b32 v10, v128, v6
	ds_bpermute_b32 v11, v128, v7
	s_waitcnt lgkmcnt(2)
	v_pk_add_f32 v[8:9], v[2:3], v[8:9]
	v_cmp_gt_i32_e32 vcc, 3, v159
	v_cndmask_b32_e64 v3, v9, v3, s[6:7]
	v_cndmask_b32_e64 v2, v8, v2, s[6:7]
	s_waitcnt lgkmcnt(0)
	v_pk_add_f32 v[10:11], v[6:7], v[10:11]
	ds_bpermute_b32 v8, v128, v2
	v_cndmask_b32_e64 v7, v11, v7, s[8:9]
	v_cndmask_b32_e64 v6, v10, v6, s[8:9]
	ds_bpermute_b32 v10, v129, v6
	ds_bpermute_b32 v11, v129, v7
	ds_bpermute_b32 v9, v128, v3
	v_cndmask_b32_e32 v18, v18, v170, vcc
	v_cmp_gt_i32_e32 vcc, 2, v159
	v_mad_i64_i32 v[18:19], s[38:39], v18, s80, v[106:107]
	s_waitcnt lgkmcnt(1)
	v_pk_add_f32 v[10:11], v[6:7], v[10:11]
	s_waitcnt lgkmcnt(0)
	v_pk_add_f32 v[8:9], v[2:3], v[8:9]
	v_cndmask_b32_e64 v7, v11, v7, s[10:11]
	v_cndmask_b32_e64 v6, v10, v6, s[10:11]
	ds_bpermute_b32 v10, v130, v6
	ds_bpermute_b32 v11, v130, v7
	v_cndmask_b32_e64 v3, v9, v3, s[8:9]
	v_cndmask_b32_e64 v2, v8, v2, s[8:9]
	ds_bpermute_b32 v8, v129, v2
	ds_bpermute_b32 v9, v129, v3
	s_waitcnt lgkmcnt(2)
	v_pk_add_f32 v[10:11], v[6:7], v[10:11]
	v_cndmask_b32_e32 v20, v20, v170, vcc
	v_cndmask_b32_e64 v7, v11, v7, s[12:13]
	v_cndmask_b32_e64 v6, v10, v6, s[12:13]
	v_pk_add_f32 v[10:11], v[12:13], v[14:15]
	v_pk_add_f32 v[14:15], v[4:5], v[16:17]
	v_cndmask_b32_e64 v11, v11, v13, s[4:5]
	v_cndmask_b32_e64 v5, v15, v5, s[4:5]
	v_cndmask_b32_e64 v4, v14, v4, s[4:5]
	v_cndmask_b32_e64 v10, v10, v12, s[4:5]
	ds_bpermute_b32 v12, v127, v10
	ds_bpermute_b32 v13, v127, v11
	ds_bpermute_b32 v14, v127, v4
	ds_bpermute_b32 v15, v127, v5
	s_waitcnt lgkmcnt(4)
	v_pk_add_f32 v[8:9], v[2:3], v[8:9]
	ds_bpermute_b32 v16, v131, v6
	s_waitcnt lgkmcnt(3)
	v_pk_add_f32 v[12:13], v[10:11], v[12:13]
	v_cndmask_b32_e64 v3, v9, v3, s[10:11]
	s_waitcnt lgkmcnt(1)
	v_pk_add_f32 v[14:15], v[4:5], v[14:15]
	v_cndmask_b32_e64 v11, v13, v11, s[6:7]
	v_cndmask_b32_e64 v5, v15, v5, s[6:7]
	v_cndmask_b32_e64 v4, v14, v4, s[6:7]
	v_cndmask_b32_e64 v10, v12, v10, s[6:7]
	ds_bpermute_b32 v12, v128, v10
	ds_bpermute_b32 v13, v128, v11
	ds_bpermute_b32 v14, v128, v4
	ds_bpermute_b32 v15, v128, v5
	v_cndmask_b32_e64 v2, v8, v2, s[10:11]
	ds_bpermute_b32 v8, v130, v2
	s_waitcnt lgkmcnt(3)
	v_pk_add_f32 v[12:13], v[10:11], v[12:13]
	ds_bpermute_b32 v9, v130, v3
	s_waitcnt lgkmcnt(2)
; __device__ __forceinline__ void gla_conv8(f32x4 (&out)[8], const bf16_t* Ug, const float* conv, int t0, int s0, int i0, int c0) {
;     f32x4 w[4];
; #pragma unroll
;     for (int j = 0; j < 4; ++j) w[j] = *(const f32x4*)(conv + j * 1024 + c0);
;     u32x2 raw[8][4];
; #pragma unroll
;     for (int e = 0; e < 8; ++e)
; #pragma unroll
;         for (int j = 0; j < 4; ++j) { const int i = i0 + 8 * e, ds = 3 - j; const bool ok = (s0 + i - ds) >= 0; raw[e][j] = *(const u32x2*)(Ug + (size_t)(ok ? t0 + i - ds : t0) * 1792 + c0); }
; __device__ __forceinline__ void gla_gcum(LAS unsigned char* lds, const GlaArgs& A, int t0, int h, int tid) {
;     ...
;     { const int lane = tid & 63, wave = tid >> 6;
; #pragma unroll
;       for (int dd = 0; dd < 8; ++dd) { const int d = wave * 8 + dd; float x = GC[lane * 65 + d];
; #pragma unroll
;           for (int o = 1; o < 64; o <<= 1) { const float y = __shfl_up(x, o); if (lane >= o) x += y; }
;           GC[lane * 65 + d] = x; } }
	v_pk_add_f32 v[14:15], v[4:5], v[14:15]
	v_cndmask_b32_e64 v11, v13, v11, s[8:9]
	v_cndmask_b32_e64 v5, v15, v5, s[8:9]
	v_cndmask_b32_e64 v4, v14, v4, s[8:9]
	v_cndmask_b32_e64 v10, v12, v10, s[8:9]
	ds_bpermute_b32 v12, v129, v10
	ds_bpermute_b32 v13, v129, v11
	ds_bpermute_b32 v14, v129, v4
	ds_bpermute_b32 v15, v129, v5
	ds_bpermute_b32 v17, v131, v7
	s_waitcnt lgkmcnt(5)
	v_pk_add_f32 v[8:9], v[2:3], v[8:9]
	s_waitcnt lgkmcnt(3)
	v_pk_add_f32 v[12:13], v[10:11], v[12:13]
	v_cndmask_b32_e64 v3, v9, v3, s[12:13]
	s_waitcnt lgkmcnt(1)
	v_pk_add_f32 v[14:15], v[4:5], v[14:15]
	v_cndmask_b32_e64 v11, v13, v11, s[10:11]
	v_cndmask_b32_e64 v5, v15, v5, s[10:11]
	v_cndmask_b32_e64 v4, v14, v4, s[10:11]
	v_cndmask_b32_e64 v10, v12, v10, s[10:11]
	ds_bpermute_b32 v12, v130, v10
	ds_bpermute_b32 v13, v130, v11
	ds_bpermute_b32 v14, v130, v4
	ds_bpermute_b32 v15, v130, v5
	v_cndmask_b32_e64 v2, v8, v2, s[12:13]
	s_waitcnt lgkmcnt(4)
	v_pk_add_f32 v[16:17], v[6:7], v[16:17]
	ds_bpermute_b32 v8, v131, v2
	ds_bpermute_b32 v9, v131, v3
	v_cndmask_b32_e64 v17, v17, v7, s[14:15]
	v_cndmask_b32_e64 v16, v16, v6, s[14:15]
	s_waitcnt lgkmcnt(4)
	v_pk_add_f32 v[6:7], v[10:11], v[12:13]
	s_waitcnt lgkmcnt(2)
	v_pk_add_f32 v[12:13], v[4:5], v[14:15]
	v_cndmask_b32_e64 v7, v7, v11, s[12:13]
	v_cndmask_b32_e64 v5, v13, v5, s[12:13]
	v_cndmask_b32_e64 v4, v12, v4, s[12:13]
	v_cndmask_b32_e64 v6, v6, v10, s[12:13]
	ds_bpermute_b32 v10, v131, v6
	ds_bpermute_b32 v11, v131, v7
	ds_bpermute_b32 v12, v131, v4
	ds_bpermute_b32 v13, v131, v5
	s_waitcnt lgkmcnt(4)
	v_pk_add_f32 v[8:9], v[2:3], v[8:9]
	v_cmp_gt_i32_e32 vcc, 1, v159
	v_cndmask_b32_e64 v3, v9, v3, s[14:15]
	v_cndmask_b32_e64 v2, v8, v2, s[14:15]
	ds_write2_b32 v145, v2, v3 offset1:1
	ds_write2_b32 v145, v16, v17 offset0:2 offset1:3
	s_waitcnt lgkmcnt(4)
	v_pk_add_f32 v[2:3], v[6:7], v[10:11]
	s_waitcnt lgkmcnt(2)
	v_pk_add_f32 v[8:9], v[4:5], v[12:13]
	v_cndmask_b32_e32 v22, v22, v170, vcc
	v_cmp_gt_i32_e32 vcc, 0, v159
	v_cndmask_b32_e64 v5, v9, v5, s[14:15]
	v_cndmask_b32_e64 v4, v8, v4, s[14:15]
	v_cndmask_b32_e64 v3, v3, v7, s[14:15]
	v_cndmask_b32_e64 v2, v2, v6, s[14:15]
	v_cndmask_b32_e32 v24, v155, v170, vcc
	ds_write2_b32 v145, v2, v3 offset0:4 offset1:5
	ds_write2_b32 v145, v4, v5 offset0:6 offset1:7
	s_waitcnt lgkmcnt(0)
	s_barrier
	global_load_dwordx4 v[14:17], v[88:89], off
	global_load_dwordx4 v[10:13], v[100:101], off
	global_load_dwordx4 v[6:9], v[102:103], off
	global_load_dwordx4 v[2:5], v[104:105], off
	v_mad_i64_i32 v[20:21], s[38:39], v20, s80, v[106:107]
	v_mad_i64_i32 v[22:23], s[38:39], v22, s80, v[106:107]
	v_mad_i64_i32 v[24:25], s[38:39], v24, s80, v[106:107]
	global_load_dwordx2 v[160:161], v[18:19], off
	global_load_dwordx2 v[162:163], v[20:21], off
	global_load_dwordx2 v[164:165], v[22:23], off
	global_load_dwordx2 v[166:167], v[24:25], off
	v_add_u32_e32 v24, 8, v159
	v_add_u32_e32 v18, 5, v155
	v_cmp_gt_i32_e32 vcc, 3, v24
	v_add_u32_e32 v20, 6, v155
	v_add_u32_e32 v22, 7, v155
	v_cndmask_b32_e32 v18, v18, v170, vcc
	v_cmp_gt_i32_e32 vcc, 2, v24
	v_mad_i64_i32 v[18:19], s[38:39], v18, s80, v[106:107]
	s_nop 0
	v_cndmask_b32_e32 v20, v20, v170, vcc
	v_cmp_gt_i32_e32 vcc, 1, v24
	v_mad_i64_i32 v[20:21], s[38:39], v20, s80, v[106:107]
	s_nop 0
	v_cndmask_b32_e32 v22, v22, v170, vcc
	v_cmp_gt_i32_e32 vcc, 0, v24
	v_mad_i64_i32 v[22:23], s[38:39], v22, s80, v[106:107]
	s_nop 0
	v_cndmask_b32_e32 v24, v111, v170, vcc
	v_mad_i64_i32 v[24:25], s[38:39], v24, s80, v[106:107]
	global_load_dwordx2 v[50:51], v[18:19], off
	global_load_dwordx2 v[38:39], v[20:21], off
	global_load_dwordx2 v[36:37], v[22:23], off
	global_load_dwordx2 v[32:33], v[24:25], off
	v_add_u32_e32 v24, 16, v159
	v_add_u32_e32 v18, 13, v155
	v_cmp_gt_i32_e32 vcc, 3, v24
	v_add_u32_e32 v20, 14, v155
	v_add_u32_e32 v22, 15, v155
	v_cndmask_b32_e32 v18, v18, v170, vcc
	v_cmp_gt_i32_e32 vcc, 2, v24
	v_mad_i64_i32 v[18:19], s[38:39], v18, s80, v[106:107]
	s_nop 0
	v_cndmask_b32_e32 v20, v20, v170, vcc
	v_cmp_gt_i32_e32 vcc, 1, v24
	v_mad_i64_i32 v[20:21], s[38:39], v20, s80, v[106:107]
	s_nop 0
	v_cndmask_b32_e32 v22, v22, v170, vcc
	v_cmp_gt_i32_e32 vcc, 0, v24
	v_mad_i64_i32 v[22:23], s[38:39], v22, s80, v[106:107]
	s_nop 0
	v_cndmask_b32_e32 v24, v110, v170, vcc
	v_mad_i64_i32 v[24:25], s[38:39], v24, s80, v[106:107]
	global_load_dwordx2 v[122:123], v[18:19], off
	global_load_dwordx2 v[120:121], v[20:21], off
	global_load_dwordx2 v[118:119], v[22:23], off
	global_load_dwordx2 v[116:117], v[24:25], off
	v_add_u32_e32 v24, 24, v159
	v_add_u32_e32 v18, 21, v155
	v_cmp_gt_i32_e32 vcc, 3, v24
	v_add_u32_e32 v20, 22, v155
	v_add_u32_e32 v22, 23, v155
	v_cndmask_b32_e32 v18, v18, v170, vcc
	v_cmp_gt_i32_e32 vcc, 2, v24
	v_mad_i64_i32 v[18:19], s[38:39], v18, s80, v[106:107]
	s_nop 0
	v_cndmask_b32_e32 v20, v20, v170, vcc
	v_cmp_gt_i32_e32 vcc, 1, v24
	v_mad_i64_i32 v[20:21], s[38:39], v20, s80, v[106:107]
	s_nop 0
	v_cndmask_b32_e32 v22, v22, v170, vcc
	v_cmp_gt_i32_e32 vcc, 0, v24
	v_mad_i64_i32 v[22:23], s[38:39], v22, s80, v[106:107]
	s_nop 0
	v_cndmask_b32_e32 v24, v109, v170, vcc
	v_mad_i64_i32 v[24:25], s[38:39], v24, s80, v[106:107]
	global_load_dwordx2 v[34:35], v[18:19], off
	global_load_dwordx2 v[30:31], v[20:21], off
	global_load_dwordx2 v[28:29], v[22:23], off
	s_nop 0
	global_load_dwordx2 v[24:25], v[24:25], off
	v_add_u32_e32 v18, 29, v155
	v_cmp_gt_i32_e32 vcc, 3, v26
	v_add_u32_e32 v20, 30, v155
	v_add_u32_e32 v22, 31, v155
	v_cndmask_b32_e32 v18, v18, v170, vcc
	v_cmp_gt_i32_e32 vcc, 2, v26
	v_mad_i64_i32 v[18:19], s[38:39], v18, s80, v[106:107]
	s_nop 0
	v_cndmask_b32_e32 v20, v20, v170, vcc
; __device__ __forceinline__ float bflo(unsigned w) { return __uint_as_float(w << 16); }
; __device__ __forceinline__ float bfhi(unsigned w) { return __uint_as_float(w & 0xffff0000u); }
; __device__ __forceinline__ float sigmoidf_(float x) { return __builtin_amdgcn_rcpf(1.0f + __expf(-x)); }
; __device__ __forceinline__ void gla_conv8(f32x4 (&out)[8], const bf16_t* Ug, const float* conv, int t0, int s0, int i0, int c0) {
;     f32x4 w[4];
; #pragma unroll
;     for (int j = 0; j < 4; ++j) w[j] = *(const f32x4*)(conv + j * 1024 + c0);
;     u32x2 raw[8][4];
; #pragma unroll
;     for (int e = 0; e < 8; ++e)
; #pragma unroll
;         for (int j = 0; j < 4; ++j) { const int i = i0 + 8 * e, ds = 3 - j; const bool ok = (s0 + i - ds) >= 0; raw[e][j] = *(const u32x2*)(Ug + (size_t)(ok ? t0 + i - ds : t0) * 1792 + c0); }
; #pragma unroll
;     for (int e = 0; e < 8; ++e) { const int i = i0 + 8 * e; f32x4 a = (f32x4){0.f, 0.f, 0.f, 0.f};
; #pragma unroll
;         for (int j = 0; j < 4; ++j) { const int ds = 3 - j; const float mk = ((s0 + i - ds) >= 0) ? 1.0f : 0.0f; const u32x2 r = raw[e][j];
;             a += (w[j] * mk) * (f32x4){bflo(r.x), bfhi(r.x), bflo(r.y), bfhi(r.y)}; }
; #pragma unroll
;         for (int q = 0; q < 4; ++q) a[q] = a[q] * sigmoidf_(a[q]);
;         out[e] = a; }
	v_cmp_gt_i32_e32 vcc, 1, v26
	v_mad_i64_i32 v[20:21], s[38:39], v20, s80, v[106:107]
	s_nop 0
	v_cndmask_b32_e32 v22, v22, v170, vcc
	v_cmp_gt_i32_e32 vcc, 0, v26
	v_mad_i64_i32 v[22:23], s[38:39], v22, s80, v[106:107]
	s_nop 0
	v_cndmask_b32_e32 v26, v108, v170, vcc
	v_mad_i64_i32 v[26:27], s[38:39], v26, s80, v[106:107]
	global_load_dwordx2 v[114:115], v[18:19], off
	global_load_dwordx2 v[112:113], v[20:21], off
	global_load_dwordx2 v[110:111], v[22:23], off
	global_load_dwordx2 v[108:109], v[26:27], off
	v_add_u32_e32 v22, 40, v159
	v_add_u32_e32 v18, 37, v155
	v_cmp_gt_i32_e32 vcc, 3, v22
	v_add_u32_e32 v20, 38, v155
	v_add_u32_e32 v23, 39, v155
	v_cndmask_b32_e32 v18, v18, v170, vcc
	v_cmp_gt_i32_e32 vcc, 2, v22
	v_mad_i64_i32 v[18:19], s[38:39], v18, s80, v[106:107]
	s_nop 0
	v_cndmask_b32_e32 v20, v20, v170, vcc
	v_cmp_gt_i32_e32 vcc, 1, v22
	v_mad_i64_i32 v[20:21], s[38:39], v20, s80, v[106:107]
	s_nop 0
	v_cndmask_b32_e32 v23, v23, v170, vcc
	v_cmp_gt_i32_e32 vcc, 0, v22
	v_mad_i64_i32 v[40:41], s[38:39], v23, s80, v[106:107]
	s_nop 0
	v_cndmask_b32_e32 v22, v158, v170, vcc
	v_add_u32_e32 v46, 48, v159
	v_mad_i64_i32 v[42:43], s[38:39], v22, s80, v[106:107]
	global_load_dwordx2 v[26:27], v[18:19], off
	global_load_dwordx2 v[22:23], v[20:21], off
	s_nop 0
	global_load_dwordx2 v[20:21], v[40:41], off
	global_load_dwordx2 v[18:19], v[42:43], off
	v_add_u32_e32 v40, 45, v155
	v_cmp_gt_i32_e32 vcc, 3, v46
	v_add_u32_e32 v42, 46, v155
	s_waitcnt vmcnt(23)
	v_and_b32_e32 v171, 0xffff0000, v160
	v_cndmask_b32_e32 v40, v40, v170, vcc
	v_cmp_gt_i32_e32 vcc, 2, v46
	v_mad_i64_i32 v[40:41], s[38:39], v40, s80, v[106:107]
	s_nop 0
	v_cndmask_b32_e32 v42, v42, v170, vcc
	v_cmp_gt_i32_e32 vcc, 1, v46
	v_mad_i64_i32 v[42:43], s[38:39], v42, s80, v[106:107]
	s_nop 0
	v_cndmask_b32_e32 v44, v44, v170, vcc
	v_cmp_gt_i32_e32 vcc, 0, v46
	v_mad_i64_i32 v[44:45], s[38:39], v44, s80, v[106:107]
	s_nop 0
	v_cndmask_b32_e32 v46, v157, v170, vcc
	v_mad_i64_i32 v[46:47], s[38:39], v46, s80, v[106:107]
	global_load_dwordx2 v[56:57], v[40:41], off
	global_load_dwordx2 v[54:55], v[42:43], off
	global_load_dwordx2 v[52:53], v[44:45], off
	global_load_dwordx2 v[48:49], v[46:47], off
	v_add_u32_e32 v44, 56, v159
	v_add_u32_e32 v40, 53, v155
	v_cmp_gt_i32_e32 vcc, 3, v44
	v_add_u32_e32 v42, 54, v155
	v_add_u32_e32 v45, 55, v155
	v_cndmask_b32_e32 v40, v40, v170, vcc
	v_cmp_gt_i32_e32 vcc, 2, v44
	v_mad_i64_i32 v[40:41], s[38:39], v40, s80, v[106:107]
	s_nop 0
	v_cndmask_b32_e32 v42, v42, v170, vcc
	v_cmp_gt_i32_e32 vcc, 1, v44
	v_mad_i64_i32 v[42:43], s[38:39], v42, s80, v[106:107]
	s_nop 0
	v_cndmask_b32_e32 v45, v45, v170, vcc
	v_cmp_gt_i32_e32 vcc, 0, v44
	v_mad_i64_i32 v[168:169], s[38:39], v45, s80, v[106:107]
	s_nop 0
	v_cndmask_b32_e32 v44, v156, v170, vcc
	v_mad_i64_i32 v[156:157], s[38:39], v44, s80, v[106:107]
	v_cmp_lt_i32_e32 vcc, 2, v159
	global_load_dwordx2 v[46:47], v[40:41], off
	global_load_dwordx2 v[44:45], v[42:43], off
	s_nop 0
	global_load_dwordx2 v[42:43], v[168:169], off
	global_load_dwordx2 v[40:41], v[156:157], off
	v_cndmask_b32_e64 v156, 0, 1.0, vcc
	v_cmp_lt_i32_e32 vcc, 1, v159
	v_pk_mul_f32 v[168:169], v[156:157], v[16:17] op_sel_hi:[0,1]
	v_pk_mul_f32 v[156:157], v[156:157], v[14:15] op_sel_hi:[0,1]
	v_lshlrev_b32_e32 v170, 16, v160
	v_lshlrev_b32_e32 v160, 16, v161
	v_and_b32_e32 v161, 0xffff0000, v161
	v_cndmask_b32_e64 v158, 0, 1.0, vcc
	v_cmp_lt_i32_e32 vcc, 0, v159
	v_pk_fma_f32 v[156:157], v[156:157], v[170:171], 0 op_sel_hi:[1,1,0]
	v_pk_fma_f32 v[160:161], v[168:169], v[160:161], 0 op_sel_hi:[1,1,0]
	v_pk_mul_f32 v[168:169], v[158:159], v[12:13] op_sel_hi:[0,1]
	v_pk_mul_f32 v[170:171], v[158:159], v[10:11] op_sel_hi:[0,1]
	s_waitcnt vmcnt(30)
	v_lshlrev_b32_e32 v172, 16, v162
	v_and_b32_e32 v173, 0xffff0000, v162
	v_lshlrev_b32_e32 v162, 16, v163
	v_and_b32_e32 v163, 0xffff0000, v163
	v_cndmask_b32_e64 v158, 0, 1.0, vcc
	v_cmp_lt_i32_e32 vcc, -1, v159
	v_pk_fma_f32 v[160:161], v[168:169], v[162:163], v[160:161]
	v_pk_fma_f32 v[156:157], v[170:171], v[172:173], v[156:157]
	v_pk_mul_f32 v[162:163], v[158:159], v[8:9] op_sel_hi:[0,1]
	v_pk_mul_f32 v[168:169], v[158:159], v[6:7] op_sel_hi:[0,1]
	s_waitcnt vmcnt(29)
	v_lshlrev_b32_e32 v170, 16, v164
	v_and_b32_e32 v171, 0xffff0000, v164
	v_lshlrev_b32_e32 v164, 16, v165
	v_and_b32_e32 v165, 0xffff0000, v165
	v_cndmask_b32_e64 v158, 0, 1.0, vcc
	v_pk_fma_f32 v[156:157], v[168:169], v[170:171], v[156:157]
	v_pk_fma_f32 v[160:161], v[162:163], v[164:165], v[160:161]
	v_pk_mul_f32 v[164:165], v[158:159], v[2:3] op_sel_hi:[0,1]
	s_waitcnt vmcnt(28)
	v_lshlrev_b32_e32 v168, 16, v166
	v_and_b32_e32 v169, 0xffff0000, v166
	v_pk_fma_f32 v[156:157], v[164:165], v[168:169], v[156:157]
	v_pk_mul_f32 v[162:163], v[158:159], v[4:5] op_sel_hi:[0,1]
	v_mul_f32_e32 v155, 0xbfb8aa3b, v156
	v_exp_f32_e32 v155, v155
	v_mul_f32_e32 v158, 0xbfb8aa3b, v157
	v_exp_f32_e32 v158, v158
	v_lshlrev_b32_e32 v166, 16, v167
	v_and_b32_e32 v167, 0xffff0000, v167
	v_pk_fma_f32 v[160:161], v[162:163], v[166:167], v[160:161]
	v_add_f32_e32 v155, 1.0, v155
	v_rcp_f32_e32 v162, v155
	v_add_f32_e32 v155, 1.0, v158
	v_mul_f32_e32 v158, 0xbfb8aa3b, v160
	v_exp_f32_e32 v158, v158
	v_mul_f32_e32 v163, 0xbfb8aa3b, v161
	v_cmp_lt_i32_e32 vcc, -6, v159
	v_exp_f32_e32 v165, v163
	v_rcp_f32_e32 v163, v155
	v_add_f32_e32 v155, 1.0, v158
	v_cndmask_b32_e64 v158, 0, 1.0, vcc
	v_cmp_lt_i32_e32 vcc, -7, v159
	v_pk_mul_f32 v[166:167], v[158:159], v[16:17] op_sel_hi:[0,1]
	v_pk_mul_f32 v[168:169], v[158:159], v[14:15] op_sel_hi:[0,1]
	s_waitcnt vmcnt(27)
; __device__ __forceinline__ float bflo(unsigned w) { return __uint_as_float(w << 16); }
; __device__ __forceinline__ float bfhi(unsigned w) { return __uint_as_float(w & 0xffff0000u); }
; __device__ __forceinline__ float sigmoidf_(float x) { return __builtin_amdgcn_rcpf(1.0f + __expf(-x)); }
; __device__ __forceinline__ void gla_conv8(f32x4 (&out)[8], const bf16_t* Ug, const float* conv, int t0, int s0, int i0, int c0) {
;     ...
;     for (int e = 0; e < 8; ++e) { const int i = i0 + 8 * e; f32x4 a = (f32x4){0.f, 0.f, 0.f, 0.f};
; #pragma unroll
;         for (int j = 0; j < 4; ++j) { const int ds = 3 - j; const float mk = ((s0 + i - ds) >= 0) ? 1.0f : 0.0f; const u32x2 r = raw[e][j];
;             a += (w[j] * mk) * (f32x4){bflo(r.x), bfhi(r.x), bflo(r.y), bfhi(r.y)}; }
; #pragma unroll
;         for (int q = 0; q < 4; ++q) a[q] = a[q] * sigmoidf_(a[q]);
;         out[e] = a; }
	v_lshlrev_b32_e32 v170, 16, v50
	v_and_b32_e32 v171, 0xffff0000, v50
	v_lshlrev_b32_e32 v50, 16, v51
	v_and_b32_e32 v51, 0xffff0000, v51
	v_cndmask_b32_e64 v158, 0, 1.0, vcc
	v_cmp_lt_i32_e32 vcc, -8, v159
	v_pk_fma_f32 v[168:169], v[168:169], v[170:171], 0 op_sel_hi:[1,1,0]
	v_pk_fma_f32 v[50:51], v[166:167], v[50:51], 0 op_sel_hi:[1,1,0]
	v_pk_mul_f32 v[166:167], v[158:159], v[12:13] op_sel_hi:[0,1]
	v_pk_mul_f32 v[170:171], v[158:159], v[10:11] op_sel_hi:[0,1]
	s_waitcnt vmcnt(26)
	v_lshlrev_b32_e32 v172, 16, v38
	v_and_b32_e32 v173, 0xffff0000, v38
	v_lshlrev_b32_e32 v38, 16, v39
	v_and_b32_e32 v39, 0xffff0000, v39
	v_cndmask_b32_e64 v158, 0, 1.0, vcc
	v_pk_fma_f32 v[38:39], v[166:167], v[38:39], v[50:51]
	v_pk_fma_f32 v[50:51], v[170:171], v[172:173], v[168:169]
	v_pk_mul_f32 v[166:167], v[158:159], v[8:9] op_sel_hi:[0,1]
	s_waitcnt vmcnt(25)
	v_lshlrev_b32_e32 v170, 16, v36
	v_and_b32_e32 v171, 0xffff0000, v36
	v_lshlrev_b32_e32 v36, 16, v37
	v_and_b32_e32 v37, 0xffff0000, v37
	v_cmp_lt_i32_e32 vcc, -9, v159
	v_pk_mul_f32 v[168:169], v[158:159], v[6:7] op_sel_hi:[0,1]
	v_pk_fma_f32 v[36:37], v[166:167], v[36:37], v[38:39]
	v_cndmask_b32_e64 v38, 0, 1.0, vcc
	v_pk_fma_f32 v[50:51], v[168:169], v[170:171], v[50:51]
	v_pk_mul_f32 v[166:167], v[38:39], v[4:5] op_sel_hi:[0,1]
	v_pk_mul_f32 v[38:39], v[38:39], v[2:3] op_sel_hi:[0,1]
	s_waitcnt vmcnt(24)
	v_lshlrev_b32_e32 v168, 16, v32
	v_and_b32_e32 v169, 0xffff0000, v32
	v_pk_fma_f32 v[168:169], v[38:39], v[168:169], v[50:51]
	v_lshlrev_b32_e32 v32, 16, v33
	v_mul_f32_e32 v38, 0xbfb8aa3b, v168
	v_exp_f32_e32 v38, v38
	v_mul_f32_e32 v39, 0xbfb8aa3b, v169
	v_exp_f32_e32 v39, v39
	v_and_b32_e32 v33, 0xffff0000, v33
	v_pk_fma_f32 v[32:33], v[166:167], v[32:33], v[36:37]
	v_add_f32_e32 v36, 1.0, v38
	v_mul_f32_e32 v38, 0xbfb8aa3b, v32
	v_add_f32_e32 v37, 1.0, v39
	v_exp_f32_e32 v38, v38
	v_mul_f32_e32 v39, 0xbfb8aa3b, v33
	v_rcp_f32_e32 v164, v155
	v_add_f32_e32 v155, 1.0, v165
	v_exp_f32_e32 v39, v39
	v_rcp_f32_e32 v165, v155
	v_add_f32_e32 v38, 1.0, v38
	v_cmp_lt_i32_e32 vcc, -14, v159
	v_rcp_f32_e32 v166, v38
	v_add_f32_e32 v38, 1.0, v39
	v_pk_mul_f32 v[50:51], v[156:157], v[162:163]
	v_cndmask_b32_e64 v156, 0, 1.0, vcc
	v_cmp_lt_i32_e32 vcc, -15, v159
	v_rcp_f32_e32 v167, v38
	v_pk_mul_f32 v[38:39], v[160:161], v[164:165]
	v_pk_mul_f32 v[160:161], v[156:157], v[16:17] op_sel_hi:[0,1]
	v_pk_mul_f32 v[156:157], v[156:157], v[14:15] op_sel_hi:[0,1]
	s_waitcnt vmcnt(23)
	v_lshlrev_b32_e32 v162, 16, v122
	v_and_b32_e32 v163, 0xffff0000, v122
	v_lshlrev_b32_e32 v122, 16, v123
	v_and_b32_e32 v123, 0xffff0000, v123
	v_cndmask_b32_e64 v158, 0, 1.0, vcc
	v_pk_fma_f32 v[156:157], v[156:157], v[162:163], 0 op_sel_hi:[1,1,0]
	v_pk_fma_f32 v[122:123], v[160:161], v[122:123], 0 op_sel_hi:[1,1,0]
	v_pk_mul_f32 v[160:161], v[158:159], v[12:13] op_sel_hi:[0,1]
	v_pk_mul_f32 v[162:163], v[158:159], v[10:11] op_sel_hi:[0,1]
	s_waitcnt vmcnt(22)
	v_lshlrev_b32_e32 v164, 16, v120
	v_and_b32_e32 v165, 0xffff0000, v120
	v_lshlrev_b32_e32 v120, 16, v121
	v_and_b32_e32 v121, 0xffff0000, v121
	v_cmp_lt_i32_e32 vcc, -16, v159
	v_pk_fma_f32 v[120:121], v[160:161], v[120:121], v[122:123]
	v_pk_fma_f32 v[122:123], v[162:163], v[164:165], v[156:157]
	v_cndmask_b32_e64 v156, 0, 1.0, vcc
	v_pk_mul_f32 v[160:161], v[156:157], v[8:9] op_sel_hi:[0,1]
	s_waitcnt vmcnt(21)
	v_lshlrev_b32_e32 v162, 16, v118
	v_and_b32_e32 v163, 0xffff0000, v118
	v_lshlrev_b32_e32 v118, 16, v119
	v_and_b32_e32 v119, 0xffff0000, v119
	v_cmp_lt_i32_e32 vcc, s36, v159
	v_pk_mul_f32 v[156:157], v[156:157], v[6:7] op_sel_hi:[0,1]
	v_pk_fma_f32 v[118:119], v[160:161], v[118:119], v[120:121]
	v_cndmask_b32_e64 v120, 0, 1.0, vcc
	s_movk_i32 s36, 0xffea
	v_pk_fma_f32 v[122:123], v[156:157], v[162:163], v[122:123]
	v_pk_mul_f32 v[156:157], v[120:121], v[4:5] op_sel_hi:[0,1]
	s_waitcnt vmcnt(20)
	v_lshlrev_b32_e32 v160, 16, v116
	v_and_b32_e32 v161, 0xffff0000, v116
	v_lshlrev_b32_e32 v116, 16, v117
	v_and_b32_e32 v117, 0xffff0000, v117
	v_cmp_lt_i32_e32 vcc, s36, v159
	s_movk_i32 s36, 0xffe9
	v_pk_mul_f32 v[120:121], v[120:121], v[2:3] op_sel_hi:[0,1]
	v_pk_fma_f32 v[116:117], v[156:157], v[116:117], v[118:119]
	v_cndmask_b32_e64 v156, 0, 1.0, vcc
	v_cmp_lt_i32_e32 vcc, s36, v159
	v_pk_fma_f32 v[120:121], v[120:121], v[160:161], v[122:123]
	v_pk_mul_f32 v[160:161], v[156:157], v[16:17] op_sel_hi:[0,1]
	v_pk_mul_f32 v[156:157], v[156:157], v[14:15] op_sel_hi:[0,1]
	s_waitcnt vmcnt(19)
	v_lshlrev_b32_e32 v162, 16, v34
	v_and_b32_e32 v163, 0xffff0000, v34
	v_lshlrev_b32_e32 v34, 16, v35
	v_and_b32_e32 v35, 0xffff0000, v35
	v_cndmask_b32_e64 v158, 0, 1.0, vcc
	s_movk_i32 s36, 0xffe8
	v_pk_fma_f32 v[156:157], v[156:157], v[162:163], 0 op_sel_hi:[1,1,0]
	v_pk_fma_f32 v[34:35], v[160:161], v[34:35], 0 op_sel_hi:[1,1,0]
	v_pk_mul_f32 v[160:161], v[158:159], v[12:13] op_sel_hi:[0,1]
	v_pk_mul_f32 v[162:163], v[158:159], v[10:11] op_sel_hi:[0,1]
	s_waitcnt vmcnt(18)
	v_lshlrev_b32_e32 v164, 16, v30
	v_and_b32_e32 v165, 0xffff0000, v30
	v_lshlrev_b32_e32 v30, 16, v31
	v_and_b32_e32 v31, 0xffff0000, v31
	v_cmp_lt_i32_e32 vcc, s36, v159
	v_pk_fma_f32 v[30:31], v[160:161], v[30:31], v[34:35]
	v_pk_fma_f32 v[34:35], v[162:163], v[164:165], v[156:157]
	v_cndmask_b32_e64 v156, 0, 1.0, vcc
	s_movk_i32 s36, 0xffe7
	v_pk_mul_f32 v[160:161], v[156:157], v[8:9] op_sel_hi:[0,1]
	s_waitcnt vmcnt(17)
; __device__ __forceinline__ float bflo(unsigned w) { return __uint_as_float(w << 16); }
; __device__ __forceinline__ float bfhi(unsigned w) { return __uint_as_float(w & 0xffff0000u); }
; __device__ __forceinline__ float sigmoidf_(float x) { return __builtin_amdgcn_rcpf(1.0f + __expf(-x)); }
; __device__ __forceinline__ void gla_conv8(f32x4 (&out)[8], const bf16_t* Ug, const float* conv, int t0, int s0, int i0, int c0) {
;     ...
;     for (int e = 0; e < 8; ++e) { const int i = i0 + 8 * e; f32x4 a = (f32x4){0.f, 0.f, 0.f, 0.f};
; #pragma unroll
;         for (int j = 0; j < 4; ++j) { const int ds = 3 - j; const float mk = ((s0 + i - ds) >= 0) ? 1.0f : 0.0f; const u32x2 r = raw[e][j];
;             a += (w[j] * mk) * (f32x4){bflo(r.x), bfhi(r.x), bflo(r.y), bfhi(r.y)}; }
; #pragma unroll
;         for (int q = 0; q < 4; ++q) a[q] = a[q] * sigmoidf_(a[q]);
;         out[e] = a; }
	v_lshlrev_b32_e32 v162, 16, v28
	v_and_b32_e32 v163, 0xffff0000, v28
	v_lshlrev_b32_e32 v28, 16, v29
	v_and_b32_e32 v29, 0xffff0000, v29
	v_cmp_lt_i32_e32 vcc, s36, v159
	v_mul_f32_e32 v122, 0xbfb8aa3b, v120
	v_mul_f32_e32 v123, 0xbfb8aa3b, v121
	v_pk_mul_f32 v[156:157], v[156:157], v[6:7] op_sel_hi:[0,1]
	v_pk_fma_f32 v[28:29], v[160:161], v[28:29], v[30:31]
	v_cndmask_b32_e64 v30, 0, 1.0, vcc
	v_exp_f32_e32 v122, v122
	v_exp_f32_e32 v123, v123
	v_pk_fma_f32 v[34:35], v[156:157], v[162:163], v[34:35]
	v_pk_mul_f32 v[156:157], v[30:31], v[4:5] op_sel_hi:[0,1]
	v_pk_mul_f32 v[30:31], v[30:31], v[2:3] op_sel_hi:[0,1]
	s_waitcnt vmcnt(16)
	v_lshlrev_b32_e32 v160, 16, v24
	v_and_b32_e32 v161, 0xffff0000, v24
	v_pk_fma_f32 v[160:161], v[30:31], v[160:161], v[34:35]
	v_add_f32_e32 v118, 1.0, v122
	v_mul_f32_e32 v30, 0xbfb8aa3b, v160
	v_exp_f32_e32 v30, v30
	v_mul_f32_e32 v31, 0xbfb8aa3b, v161
	v_add_f32_e32 v119, 1.0, v123
	v_mul_f32_e32 v122, 0xbfb8aa3b, v116
	v_mul_f32_e32 v123, 0xbfb8aa3b, v117
	v_exp_f32_e32 v31, v31
	v_exp_f32_e32 v122, v122
	v_exp_f32_e32 v123, v123
	v_lshlrev_b32_e32 v24, 16, v25
	v_and_b32_e32 v25, 0xffff0000, v25
	v_pk_fma_f32 v[24:25], v[156:157], v[24:25], v[28:29]
	v_add_f32_e32 v28, 1.0, v30
	v_mul_f32_e32 v30, 0xbfb8aa3b, v24
	v_add_f32_e32 v29, 1.0, v31
	v_exp_f32_e32 v30, v30
	v_mul_f32_e32 v31, 0xbfb8aa3b, v25
	v_add_f32_e32 v122, 1.0, v122
	v_add_f32_e32 v123, 1.0, v123
	v_exp_f32_e32 v31, v31
	v_rcp_f32_e32 v122, v122
	v_rcp_f32_e32 v123, v123
	v_rcp_f32_e32 v118, v118
	v_rcp_f32_e32 v119, v119
	v_add_f32_e32 v30, 1.0, v30
	s_movk_i32 s36, 0xffe2
	v_rcp_f32_e32 v156, v30
	v_add_f32_e32 v30, 1.0, v31
	v_cmp_lt_i32_e32 vcc, s36, v159
	v_rcp_f32_e32 v157, v30
	v_pk_mul_f32 v[30:31], v[116:117], v[122:123]
	v_cndmask_b32_e64 v116, 0, 1.0, vcc
	v_pk_mul_f32 v[34:35], v[120:121], v[118:119]
	v_pk_mul_f32 v[118:119], v[116:117], v[16:17] op_sel_hi:[0,1]
	s_waitcnt vmcnt(15)
	v_lshlrev_b32_e32 v120, 16, v114
	v_and_b32_e32 v121, 0xffff0000, v114
	v_lshlrev_b32_e32 v114, 16, v115
	v_and_b32_e32 v115, 0xffff0000, v115
	v_cmp_lt_i32_e32 vcc, s83, v159
	v_pk_mul_f32 v[116:117], v[116:117], v[14:15] op_sel_hi:[0,1]
	v_pk_fma_f32 v[114:115], v[118:119], v[114:115], 0 op_sel_hi:[1,1,0]
	v_cndmask_b32_e64 v118, 0, 1.0, vcc
	s_movk_i32 s36, 0xffe0
	v_pk_fma_f32 v[116:117], v[116:117], v[120:121], 0 op_sel_hi:[1,1,0]
	v_pk_mul_f32 v[120:121], v[118:119], v[12:13] op_sel_hi:[0,1]
	v_pk_mul_f32 v[118:119], v[118:119], v[10:11] op_sel_hi:[0,1]
	s_waitcnt vmcnt(14)
	v_lshlrev_b32_e32 v122, 16, v112
	v_and_b32_e32 v123, 0xffff0000, v112
	v_lshlrev_b32_e32 v112, 16, v113
	v_and_b32_e32 v113, 0xffff0000, v113
	v_cmp_lt_i32_e32 vcc, s36, v159
	v_pk_fma_f32 v[112:113], v[120:121], v[112:113], v[114:115]
	v_pk_fma_f32 v[114:115], v[118:119], v[122:123], v[116:117]
	v_cndmask_b32_e64 v116, 0, 1.0, vcc
	s_movk_i32 s36, 0xffdf
	v_pk_mul_f32 v[118:119], v[116:117], v[8:9] op_sel_hi:[0,1]
	s_waitcnt vmcnt(13)
	v_lshlrev_b32_e32 v120, 16, v110
	v_and_b32_e32 v121, 0xffff0000, v110
	v_lshlrev_b32_e32 v110, 16, v111
	v_and_b32_e32 v111, 0xffff0000, v111
	v_cmp_lt_i32_e32 vcc, s36, v159
	v_pk_mul_f32 v[116:117], v[116:117], v[6:7] op_sel_hi:[0,1]
	v_pk_fma_f32 v[110:111], v[118:119], v[110:111], v[112:113]
	v_cndmask_b32_e64 v112, 0, 1.0, vcc
	s_movk_i32 s36, 0xffda
	v_pk_fma_f32 v[114:115], v[116:117], v[120:121], v[114:115]
	v_pk_mul_f32 v[116:117], v[112:113], v[4:5] op_sel_hi:[0,1]
	s_waitcnt vmcnt(12)
	v_lshlrev_b32_e32 v118, 16, v108
	v_and_b32_e32 v119, 0xffff0000, v108
	v_lshlrev_b32_e32 v108, 16, v109
	v_and_b32_e32 v109, 0xffff0000, v109
	v_cmp_lt_i32_e32 vcc, s36, v159
	v_pk_mul_f32 v[112:113], v[112:113], v[2:3] op_sel_hi:[0,1]
	v_pk_fma_f32 v[108:109], v[116:117], v[108:109], v[110:111]
	v_cndmask_b32_e64 v116, 0, 1.0, vcc
	s_movk_i32 s36, 0xffd9
	v_pk_fma_f32 v[112:113], v[112:113], v[118:119], v[114:115]
	v_pk_mul_f32 v[118:119], v[116:117], v[16:17] op_sel_hi:[0,1]
	s_waitcnt vmcnt(11)
	v_lshlrev_b32_e32 v120, 16, v26
	v_and_b32_e32 v121, 0xffff0000, v26
	v_lshlrev_b32_e32 v26, 16, v27
	v_and_b32_e32 v27, 0xffff0000, v27
	v_cmp_lt_i32_e32 vcc, s36, v159
	v_pk_mul_f32 v[116:117], v[116:117], v[14:15] op_sel_hi:[0,1]
	v_pk_fma_f32 v[26:27], v[118:119], v[26:27], 0 op_sel_hi:[1,1,0]
	v_cndmask_b32_e64 v118, 0, 1.0, vcc
	s_movk_i32 s36, 0xffd8
	v_pk_fma_f32 v[116:117], v[116:117], v[120:121], 0 op_sel_hi:[1,1,0]
	v_pk_mul_f32 v[120:121], v[118:119], v[12:13] op_sel_hi:[0,1]
	v_pk_mul_f32 v[118:119], v[118:119], v[10:11] op_sel_hi:[0,1]
	s_waitcnt vmcnt(10)
	v_lshlrev_b32_e32 v122, 16, v22
	v_and_b32_e32 v123, 0xffff0000, v22
	v_lshlrev_b32_e32 v22, 16, v23
	v_and_b32_e32 v23, 0xffff0000, v23
	v_cmp_lt_i32_e32 vcc, s36, v159
	v_pk_fma_f32 v[22:23], v[120:121], v[22:23], v[26:27]
	v_pk_fma_f32 v[26:27], v[118:119], v[122:123], v[116:117]
	v_cndmask_b32_e64 v116, 0, 1.0, vcc
	s_movk_i32 s36, 0xffd7
	v_pk_mul_f32 v[118:119], v[116:117], v[8:9] op_sel_hi:[0,1]
	s_waitcnt vmcnt(9)
	v_lshlrev_b32_e32 v120, 16, v20
	v_and_b32_e32 v121, 0xffff0000, v20
	v_lshlrev_b32_e32 v20, 16, v21
	v_and_b32_e32 v21, 0xffff0000, v21
	v_cmp_lt_i32_e32 vcc, s36, v159
	v_mul_f32_e32 v114, 0xbfb8aa3b, v112
	v_mul_f32_e32 v115, 0xbfb8aa3b, v113
	v_pk_mul_f32 v[116:117], v[116:117], v[6:7] op_sel_hi:[0,1]
	v_pk_fma_f32 v[20:21], v[118:119], v[20:21], v[22:23]
	v_cndmask_b32_e64 v22, 0, 1.0, vcc
	v_exp_f32_e32 v114, v114
	v_exp_f32_e32 v115, v115
	v_pk_fma_f32 v[26:27], v[116:117], v[120:121], v[26:27]
	v_pk_mul_f32 v[116:117], v[22:23], v[4:5] op_sel_hi:[0,1]
	v_pk_mul_f32 v[22:23], v[22:23], v[2:3] op_sel_hi:[0,1]
	s_waitcnt vmcnt(8)
; #define LAS __attribute__((address_space(3)))
; __device__ __forceinline__ unsigned cvt_pk_bf16(float lo, float hi) { const f32x2 v = {lo, hi}; const bf16x2_t r = __builtin_convertvector(v, bf16x2_t); return __builtin_bit_cast(unsigned, r); }
; __device__ __forceinline__ float bflo(unsigned w) { return __uint_as_float(w << 16); }
; __device__ __forceinline__ float bfhi(unsigned w) { return __uint_as_float(w & 0xffff0000u); }
; __device__ __forceinline__ float sigmoidf_(float x) { return __builtin_amdgcn_rcpf(1.0f + __expf(-x)); }
; __device__ __forceinline__ void gla_conv8(f32x4 (&out)[8], const bf16_t* Ug, const float* conv, int t0, int s0, int i0, int c0) {
;     ...
;     for (int e = 0; e < 8; ++e) { const int i = i0 + 8 * e; f32x4 a = (f32x4){0.f, 0.f, 0.f, 0.f};
; #pragma unroll
;         for (int j = 0; j < 4; ++j) { const int ds = 3 - j; const float mk = ((s0 + i - ds) >= 0) ? 1.0f : 0.0f; const u32x2 r = raw[e][j];
;             a += (w[j] * mk) * (f32x4){bflo(r.x), bfhi(r.x), bflo(r.y), bfhi(r.y)}; }
; #pragma unroll
;         for (int q = 0; q < 4; ++q) a[q] = a[q] * sigmoidf_(a[q]);
;         out[e] = a; }
; __device__ __forceinline__ void gla_c_tile(LAS unsigned char* lds, const GlaArgs& A, int tile, int tid) {
;     ...
;       if (cc < 128) { const int d = cc & 63; const bool isq = cc < 64; LAS bf16_t* T1 = isq ? QG : KR; LAS bf16_t* T2 = isq ? QR : KG; const float sc = isq ? 0.125f : 1.0f;
; #pragma unroll
;           for (int e = 0; e < 8; ++e) { const int i = i0 + 8 * e; f32x4 x1, x2;
; #pragma unroll
;               for (int q = 0; q < 4; ++q) { const float eg = __expf(GC[i * 65 + d + q]); const float x = o[e][q] * sc; x1[q] = x * eg; x2[q] = x / eg; }
;               u32x2 w1, w2; w1.x = cvt_pk_bf16(x1[0], x1[1]); w1.y = cvt_pk_bf16(x1[2], x1[3]); w2.x = cvt_pk_bf16(x2[0], x2[1]); w2.y = cvt_pk_bf16(x2[2], x2[3]);
;               *(LAS u32x2*)(T1 + i * 72 + d) = w1; *(LAS u32x2*)(T2 + i * 72 + d) = w2; } }
;       else { const int ev = cc - 128;
	v_lshlrev_b32_e32 v118, 16, v18
	v_and_b32_e32 v119, 0xffff0000, v18
	v_pk_fma_f32 v[118:119], v[22:23], v[118:119], v[26:27]
	v_add_f32_e32 v110, 1.0, v114
	v_mul_f32_e32 v22, 0xbfb8aa3b, v118
	v_exp_f32_e32 v22, v22
	v_mul_f32_e32 v23, 0xbfb8aa3b, v119
	v_add_f32_e32 v111, 1.0, v115
	v_mul_f32_e32 v114, 0xbfb8aa3b, v108
	v_mul_f32_e32 v115, 0xbfb8aa3b, v109
	v_exp_f32_e32 v23, v23
	v_exp_f32_e32 v114, v114
	v_exp_f32_e32 v115, v115
	v_lshlrev_b32_e32 v18, 16, v19
	v_and_b32_e32 v19, 0xffff0000, v19
	v_pk_fma_f32 v[18:19], v[116:117], v[18:19], v[20:21]
	v_add_f32_e32 v20, 1.0, v22
	v_mul_f32_e32 v22, 0xbfb8aa3b, v18
	v_add_f32_e32 v21, 1.0, v23
	v_exp_f32_e32 v22, v22
	v_mul_f32_e32 v23, 0xbfb8aa3b, v19
	v_add_f32_e32 v114, 1.0, v114
	v_add_f32_e32 v115, 1.0, v115
	v_exp_f32_e32 v23, v23
	v_rcp_f32_e32 v114, v114
	v_rcp_f32_e32 v115, v115
	v_rcp_f32_e32 v110, v110
	v_rcp_f32_e32 v111, v111
	v_add_f32_e32 v22, 1.0, v22
	s_movk_i32 s36, 0xffd2
	v_rcp_f32_e32 v116, v22
	v_add_f32_e32 v22, 1.0, v23
	v_cmp_lt_i32_e32 vcc, s36, v159
	v_rcp_f32_e32 v117, v22
	v_pk_mul_f32 v[22:23], v[108:109], v[114:115]
	v_cndmask_b32_e64 v108, 0, 1.0, vcc
	s_movk_i32 s36, 0xffd1
	v_pk_mul_f32 v[26:27], v[112:113], v[110:111]
	v_pk_mul_f32 v[110:111], v[108:109], v[16:17] op_sel_hi:[0,1]
	s_waitcnt vmcnt(7)
	v_lshlrev_b32_e32 v112, 16, v56
	v_and_b32_e32 v113, 0xffff0000, v56
	v_lshlrev_b32_e32 v56, 16, v57
	v_and_b32_e32 v57, 0xffff0000, v57
	v_cmp_lt_i32_e32 vcc, s36, v159
	v_pk_mul_f32 v[108:109], v[108:109], v[14:15] op_sel_hi:[0,1]
	v_pk_fma_f32 v[56:57], v[110:111], v[56:57], 0 op_sel_hi:[1,1,0]
	v_cndmask_b32_e64 v110, 0, 1.0, vcc
	s_movk_i32 s36, 0xffd0
	v_pk_fma_f32 v[108:109], v[108:109], v[112:113], 0 op_sel_hi:[1,1,0]
	v_pk_mul_f32 v[112:113], v[110:111], v[12:13] op_sel_hi:[0,1]
	v_pk_mul_f32 v[110:111], v[110:111], v[10:11] op_sel_hi:[0,1]
	s_waitcnt vmcnt(6)
	v_lshlrev_b32_e32 v114, 16, v54
	v_and_b32_e32 v115, 0xffff0000, v54
	v_lshlrev_b32_e32 v54, 16, v55
	v_and_b32_e32 v55, 0xffff0000, v55
	v_cmp_lt_i32_e32 vcc, s36, v159
	v_pk_fma_f32 v[54:55], v[112:113], v[54:55], v[56:57]
	v_pk_fma_f32 v[56:57], v[110:111], v[114:115], v[108:109]
	v_cndmask_b32_e64 v108, 0, 1.0, vcc
	s_movk_i32 s36, 0xffcf
	v_pk_mul_f32 v[110:111], v[108:109], v[8:9] op_sel_hi:[0,1]
	s_waitcnt vmcnt(5)
	v_lshlrev_b32_e32 v112, 16, v52
	v_and_b32_e32 v113, 0xffff0000, v52
	v_lshlrev_b32_e32 v52, 16, v53
	v_and_b32_e32 v53, 0xffff0000, v53
	v_cmp_lt_i32_e32 vcc, s36, v159
	v_pk_mul_f32 v[108:109], v[108:109], v[6:7] op_sel_hi:[0,1]
	v_pk_fma_f32 v[52:53], v[110:111], v[52:53], v[54:55]
	v_cndmask_b32_e64 v54, 0, 1.0, vcc
	s_movk_i32 s36, 0xffca
	v_pk_fma_f32 v[56:57], v[108:109], v[112:113], v[56:57]
	v_pk_mul_f32 v[108:109], v[54:55], v[4:5] op_sel_hi:[0,1]
	s_waitcnt vmcnt(4)
	v_lshlrev_b32_e32 v110, 16, v48
	v_and_b32_e32 v111, 0xffff0000, v48
	v_lshlrev_b32_e32 v48, 16, v49
	v_and_b32_e32 v49, 0xffff0000, v49
	v_cmp_lt_i32_e32 vcc, s36, v159
	v_pk_fma_f32 v[48:49], v[108:109], v[48:49], v[52:53]
	s_movk_i32 s36, 0xffc9
	v_cndmask_b32_e64 v108, 0, 1.0, vcc
	v_pk_mul_f32 v[16:17], v[108:109], v[16:17] op_sel_hi:[0,1]
	v_pk_mul_f32 v[14:15], v[108:109], v[14:15] op_sel_hi:[0,1]
	s_waitcnt vmcnt(3)
	v_lshlrev_b32_e32 v108, 16, v46
	v_and_b32_e32 v109, 0xffff0000, v46
	v_lshlrev_b32_e32 v46, 16, v47
	v_and_b32_e32 v47, 0xffff0000, v47
	v_cmp_lt_i32_e32 vcc, s36, v159
	v_pk_fma_f32 v[16:17], v[16:17], v[46:47], 0 op_sel_hi:[1,1,0]
	s_movk_i32 s36, 0xffc8
	v_cndmask_b32_e64 v46, 0, 1.0, vcc
	v_pk_fma_f32 v[14:15], v[14:15], v[108:109], 0 op_sel_hi:[1,1,0]
	v_pk_mul_f32 v[12:13], v[46:47], v[12:13] op_sel_hi:[0,1]
	v_pk_mul_f32 v[10:11], v[46:47], v[10:11] op_sel_hi:[0,1]
	s_waitcnt vmcnt(2)
	v_lshlrev_b32_e32 v46, 16, v44
	v_and_b32_e32 v47, 0xffff0000, v44
	v_cmp_lt_i32_e32 vcc, s36, v159
	v_pk_fma_f32 v[10:11], v[10:11], v[46:47], v[14:15]
	s_movk_i32 s36, 0xffc7
	v_cndmask_b32_e64 v14, 0, 1.0, vcc
	v_pk_mul_f32 v[8:9], v[14:15], v[8:9] op_sel_hi:[0,1]
	v_pk_mul_f32 v[6:7], v[14:15], v[6:7] op_sel_hi:[0,1]
	s_waitcnt vmcnt(1)
	v_lshlrev_b32_e32 v14, 16, v42
	v_and_b32_e32 v15, 0xffff0000, v42
	v_cmp_lt_i32_e32 vcc, s36, v159
	v_pk_fma_f32 v[6:7], v[6:7], v[14:15], v[10:11]
	v_pk_mul_f32 v[54:55], v[54:55], v[2:3] op_sel_hi:[0,1]
	v_cndmask_b32_e64 v10, 0, 1.0, vcc
	v_pk_mul_f32 v[4:5], v[10:11], v[4:5] op_sel_hi:[0,1]
	v_pk_mul_f32 v[2:3], v[10:11], v[2:3] op_sel_hi:[0,1]
	s_waitcnt vmcnt(0)
	v_lshlrev_b32_e32 v10, 16, v40
	v_and_b32_e32 v11, 0xffff0000, v40
	v_pk_fma_f32 v[2:3], v[2:3], v[10:11], v[6:7]
	v_pk_fma_f32 v[54:55], v[54:55], v[110:111], v[56:57]
	v_mul_f32_e32 v6, 0xbfb8aa3b, v2
	v_mul_f32_e32 v56, 0xbfb8aa3b, v54
	v_mul_f32_e32 v57, 0xbfb8aa3b, v55
	v_lshlrev_b32_e32 v44, 16, v45
	v_and_b32_e32 v45, 0xffff0000, v45
	v_exp_f32_e32 v6, v6
	v_mul_f32_e32 v7, 0xbfb8aa3b, v3
	v_exp_f32_e32 v56, v56
	v_exp_f32_e32 v57, v57
	v_pk_fma_f32 v[12:13], v[12:13], v[44:45], v[16:17]
	v_lshlrev_b32_e32 v16, 16, v43
	v_and_b32_e32 v17, 0xffff0000, v43
	v_exp_f32_e32 v7, v7
	v_pk_fma_f32 v[8:9], v[8:9], v[16:17], v[12:13]
	v_lshlrev_b32_e32 v12, 16, v41
	v_and_b32_e32 v13, 0xffff0000, v41
	v_pk_fma_f32 v[10:11], v[4:5], v[12:13], v[8:9]
	v_add_f32_e32 v4, 1.0, v6
	v_mul_f32_e32 v6, 0xbfb8aa3b, v10
	v_add_f32_e32 v52, 1.0, v56
	v_add_f32_e32 v53, 1.0, v57
	v_mul_f32_e32 v56, 0xbfb8aa3b, v48
	v_mul_f32_e32 v57, 0xbfb8aa3b, v49
	v_add_f32_e32 v5, 1.0, v7
	v_exp_f32_e32 v6, v6
	v_mul_f32_e32 v7, 0xbfb8aa3b, v11
	v_exp_f32_e32 v56, v56
	v_exp_f32_e32 v57, v57
	v_exp_f32_e32 v7, v7
	v_add_f32_e32 v6, 1.0, v6
	v_add_f32_e32 v56, 1.0, v56
	v_add_f32_e32 v57, 1.0, v57
	v_rcp_f32_e32 v12, v6
	v_add_f32_e32 v6, 1.0, v7
	v_rcp_f32_e32 v36, v36
	v_rcp_f32_e32 v37, v37
	v_rcp_f32_e32 v28, v28
	v_rcp_f32_e32 v29, v29
	v_rcp_f32_e32 v20, v20
	v_rcp_f32_e32 v21, v21
	v_rcp_f32_e32 v52, v52
	v_rcp_f32_e32 v53, v53
	v_rcp_f32_e32 v56, v56
	v_rcp_f32_e32 v57, v57
	v_rcp_f32_e32 v4, v4
	v_rcp_f32_e32 v5, v5
	v_rcp_f32_e32 v13, v6
	v_pk_mul_f32 v[36:37], v[168:169], v[36:37]
	v_pk_mul_f32 v[32:33], v[32:33], v[166:167]
	v_pk_mul_f32 v[28:29], v[160:161], v[28:29]
	v_pk_mul_f32 v[24:25], v[24:25], v[156:157]
	v_pk_mul_f32 v[20:21], v[118:119], v[20:21]
	v_pk_mul_f32 v[18:19], v[18:19], v[116:117]
	v_pk_mul_f32 v[8:9], v[54:55], v[52:53]
	v_pk_mul_f32 v[6:7], v[48:49], v[56:57]
	v_pk_mul_f32 v[4:5], v[2:3], v[4:5]
	v_pk_mul_f32 v[2:3], v[10:11], v[12:13]
	s_and_saveexec_b64 s[38:39], s[16:17]
	s_xor_b64 s[38:39], exec, s[38:39]
	s_cbranch_execz .LBB0_312
; __device__ __forceinline__ bf16_t f2bf(float x) { return (bf16_t)(cvt_pk_bf16(x, 0.f) & 0xffffu); }
; __device__ __forceinline__ void gla_c_tile(LAS unsigned char* lds, const GlaArgs& A, int tile, int tid) {
;     ...
;       else { const int ev = cc - 128;
; #pragma unroll
;           for (int e = 0; e < 8; ++e) { const int i = i0 + 8 * e;
; #pragma unroll
;               for (int q = 0; q < 4; ++q) VT[(ev + q) * 72 + i] = f2bf(o[e][q]); } } }
	v_cvt_pk_bf16_f32 v10, v50, s0
	ds_write_b16 v146, v10 offset:35072
	v_cvt_pk_bf16_f32 v10, v51, s0
	ds_write_b16 v146, v10 offset:35216
	v_cvt_pk_bf16_f32 v10, v38, s0
	ds_write_b16 v146, v10 offset:35360
	v_cvt_pk_bf16_f32 v10, v39, s0
	ds_write_b16 v146, v10 offset:35504
	v_cvt_pk_bf16_f32 v10, v36, s0
	ds_write_b16 v146, v10 offset:35088
	v_cvt_pk_bf16_f32 v10, v37, s0
	ds_write_b16 v146, v10 offset:35232
	v_cvt_pk_bf16_f32 v10, v32, s0
	ds_write_b16 v146, v10 offset:35376
	v_cvt_pk_bf16_f32 v10, v33, s0
	ds_write_b16 v146, v10 offset:35520
	v_cvt_pk_bf16_f32 v10, v34, s0
	ds_write_b16 v146, v10 offset:35104
	v_cvt_pk_bf16_f32 v10, v35, s0
	ds_write_b16 v146, v10 offset:35248
	v_cvt_pk_bf16_f32 v10, v30, s0
	ds_write_b16 v146, v10 offset:35392
	v_cvt_pk_bf16_f32 v10, v31, s0
	ds_write_b16 v146, v10 offset:35536
	v_cvt_pk_bf16_f32 v10, v28, s0
	ds_write_b16 v146, v10 offset:35120
	v_cvt_pk_bf16_f32 v10, v29, s0
	ds_write_b16 v146, v10 offset:35264
	v_cvt_pk_bf16_f32 v10, v24, s0
	ds_write_b16 v146, v10 offset:35408
	v_cvt_pk_bf16_f32 v10, v25, s0
	ds_write_b16 v146, v10 offset:35552
	v_cvt_pk_bf16_f32 v10, v26, s0
	ds_write_b16 v146, v10 offset:35136
	v_cvt_pk_bf16_f32 v10, v27, s0
	ds_write_b16 v146, v10 offset:35280
	v_cvt_pk_bf16_f32 v10, v22, s0
	ds_write_b16 v146, v10 offset:35424
	v_cvt_pk_bf16_f32 v10, v23, s0
	ds_write_b16 v146, v10 offset:35568
	v_cvt_pk_bf16_f32 v10, v20, s0
	ds_write_b16 v146, v10 offset:35152
	v_cvt_pk_bf16_f32 v10, v21, s0
	ds_write_b16 v146, v10 offset:35296
	v_cvt_pk_bf16_f32 v10, v18, s0
	v_cvt_pk_bf16_f32 v8, v8, s0
	v_cvt_pk_bf16_f32 v6, v6, s0
	v_cvt_pk_bf16_f32 v4, v4, s0
	v_cvt_pk_bf16_f32 v2, v2, s0
	ds_write_b16 v146, v10 offset:35440
	v_cvt_pk_bf16_f32 v10, v19, s0
	ds_write_b16 v146, v8 offset:35168
	v_cvt_pk_bf16_f32 v8, v9, s0
	ds_write_b16 v146, v6 offset:35456
	v_cvt_pk_bf16_f32 v6, v7, s0
	ds_write_b16 v146, v4 offset:35184
	v_cvt_pk_bf16_f32 v4, v5, s0
	ds_write_b16 v146, v2 offset:35472
	v_cvt_pk_bf16_f32 v2, v3, s0
	ds_write_b16 v146, v10 offset:35584
	ds_write_b16 v146, v8 offset:35312
	ds_write_b16 v146, v6 offset:35600
	ds_write_b16 v146, v4 offset:35328
	ds_write_b16 v146, v2 offset:35616

; #define LAS __attribute__((address_space(3)))
; __device__ __forceinline__ unsigned cvt_pk_bf16(float lo, float hi) { const f32x2 v = {lo, hi}; const bf16x2_t r = __builtin_convertvector(v, bf16x2_t); return __builtin_bit_cast(unsigned, r); }
; __device__ __forceinline__ void gla_c_tile(LAS unsigned char* lds, const GlaArgs& A, int tile, int tid) {
;     ...
;     const int lane = tid & 63, wave = tid >> 6, fr = lane & 15, fq = lane >> 4; const int mt = wave >> 1;
;     {
; #pragma unroll
;         for (int q = 0; q < 2; ++q) { const int nt = (wave & 1) * 2 + q; f32x4 ap = (f32x4){0.f, 0.f, 0.f, 0.f}, af = ap;
; #pragma unroll
;             for (int ks = 0; ks < 2; ++ks) { const int ko = ks * 32 + fq * 8;
;                 ap = mfma16(*(LAS const bf16x8*)(KG + (16 * nt + fr) * 72 + ko), *(LAS const bf16x8*)(QG + (16 * mt + fr) * 72 + ko), ap);
;                 af = mfma16(*(LAS const bf16x8*)(KR + (16 * nt + fr) * 72 + ko), *(LAS const bf16x8*)(QR + (16 * mt + fr) * 72 + ko), af); }
;             const int trow = 16 * mt + fr; f32x4 o;
; #pragma unroll
;             for (int j = 0; j < 4; ++j) { const int scol = 16 * nt + 4 * fq + j; o[j] = (scol <= trow) ? ap[j] : af[j]; }
;             u32x2 w; w.x = cvt_pk_bf16(o[0], o[1]); w.y = cvt_pk_bf16(o[2], o[3]); *(LAS u32x2*)(AL + trow * 72 + 16 * nt + 4 * fq) = w; }
;     }
;     __syncthreads();
;     f32x4 acc[4];
; #pragma unroll
;     for (int q = 0; q < 4; ++q) acc[q] = (f32x4){0.f, 0.f, 0.f, 0.f};
;     const bf16_t* sp = A.spT + ((size_t)bh * 64 + n) * 128 * 64;
; #pragma unroll
;     for (int ks = 0; ks < 2; ++ks) { const int ko = ks * 32 + fq * 8; const bf16x8 a1 = *(LAS const bf16x8*)(AL + (16 * mt + fr) * 72 + ko), a2 = *(LAS const bf16x8*)(QG + (16 * mt + fr) * 72 + ko);
; #pragma unroll
;         for (int q = 0; q < 4; ++q) { const int nt = (wave & 1) * 4 + q;
;             acc[q] = mfma16(*(LAS const bf16x8*)(VT + (16 * nt + fr) * 72 + ko), a1, acc[q]);
;             acc[q] = mfma16(*(const bf16x8*)(sp + (size_t)(16 * nt + fr) * 64 + ko), a2, acc[q]); } }
;     float ssq = 0.f;
; #pragma unroll
;     for (int q = 0; q < 4; ++q) ssq += (acc[q][0] * acc[q][0] + acc[q][1] * acc[q][1]) + (acc[q][2] * acc[q][2] + acc[q][3] * acc[q][3]);
;     ssq += __shfl_xor(ssq, 16); ssq += __shfl_xor(ssq, 32);
;     if (fq == 0) RS[(16 * mt + fr) * 2 + (wave & 1)] = ssq;
.LBB0_314:
	s_or_b64 exec, exec, s[38:39]
	s_waitcnt lgkmcnt(0)
	s_barrier
	ds_read_b128 v[2:5], v135 offset:25856
	ds_read_b128 v[6:9], v136 offset:16640
	ds_read_b128 v[10:13], v135 offset:44288
	ds_read_b128 v[14:17], v136 offset:35072
	ds_read_b128 v[18:21], v135 offset:25920
	ds_read_b128 v[22:25], v136 offset:16704
	s_waitcnt lgkmcnt(4)
	v_mfma_f32_16x16x32_bf16 v[2:5], v[2:5], v[6:9], 0
	s_mov_b32 s36, 0x18100000
	s_waitcnt lgkmcnt(0)
	v_mfma_f32_16x16x32_bf16 v[2:5], v[18:21], v[22:25], v[2:5]
	ds_read_b128 v[18:21], v135 offset:44352
	ds_read_b128 v[26:29], v136 offset:35136
	v_mfma_f32_16x16x32_bf16 v[10:13], v[10:13], v[14:17], 0
	s_waitcnt lgkmcnt(0)
	v_mfma_f32_16x16x32_bf16 v[10:13], v[18:21], v[26:29], v[10:13]
	v_lshl_add_u64 v[18:19], v[94:95], 0, s[52:53]
	s_nop 6
	v_cndmask_b32_e64 v2, v2, v10, s[18:19]
	v_cndmask_b32_e64 v3, v11, v3, s[20:21]
	v_cndmask_b32_e64 v4, v4, v12, s[22:23]
	v_cndmask_b32_e64 v5, v5, v13, s[24:25]
	v_cvt_pk_bf16_f32 v2, v2, v3
	v_cvt_pk_bf16_f32 v3, v4, v5
	ds_write_b64 v148, v[2:3]
	ds_read_b128 v[2:5], v137 offset:25856
	ds_read_b128 v[10:13], v137 offset:25920
	s_waitcnt lgkmcnt(1)
	v_mfma_f32_16x16x32_bf16 v[2:5], v[2:5], v[6:9], 0
	ds_read_b128 v[6:9], v137 offset:44288
	s_waitcnt lgkmcnt(1)
	v_mfma_f32_16x16x32_bf16 v[2:5], v[10:13], v[22:25], v[2:5]
	ds_read_b128 v[10:13], v137 offset:44352
	v_lshl_add_u64 v[22:23], v[92:93], 0, s[52:53]
	s_waitcnt lgkmcnt(1)
	v_mfma_f32_16x16x32_bf16 v[6:9], v[6:9], v[14:17], 0
	v_lshl_add_u64 v[14:15], v[96:97], 0, s[52:53]
	v_add_co_u32_e32 v34, vcc, s36, v14
	s_waitcnt lgkmcnt(0)
	v_mfma_f32_16x16x32_bf16 v[6:9], v[10:13], v[26:29], v[6:9]
	v_addc_co_u32_e32 v35, vcc, 0, v15, vcc
	v_add_co_u32_e32 v36, vcc, s36, v18
	s_nop 1
	v_addc_co_u32_e32 v37, vcc, 0, v19, vcc
	s_nop 2
	v_cndmask_b32_e64 v2, v2, v6, s[26:27]
	v_cndmask_b32_e64 v3, v7, v3, s[28:29]
	v_cndmask_b32_e64 v4, v4, v8, s[30:31]
	v_cndmask_b32_e64 v5, v5, v9, s[34:35]
	v_cvt_pk_bf16_f32 v2, v2, v3
	v_cvt_pk_bf16_f32 v3, v4, v5
	ds_write_b64 v149, v[2:3]
	s_waitcnt lgkmcnt(0)
	s_barrier
	ds_read_b128 v[26:29], v138
	ds_read_b128 v[30:33], v136 offset:16640
	ds_read_b128 v[42:45], v150 offset:53504
	ds_read_b128 v[46:49], v151 offset:53504
	ds_read_b128 v[50:53], v152 offset:53504
	ds_read_b128 v[54:57], v153 offset:53504
	ds_read_b128 v[34:37], v138 offset:64
	ds_read_b128 v[38:41], v136 offset:16704
	ds_read_b128 v[212:215], v150 offset:53568
	ds_read_b128 v[216:219], v151 offset:53568
	ds_read_b128 v[220:223], v152 offset:53568
	ds_read_b128 v[224:227], v153 offset:53568
	s_waitcnt lgkmcnt(9)
	v_mfma_f32_16x16x32_bf16 v[14:17], v[42:45], v[26:29], 0
	s_waitcnt lgkmcnt(8)
	v_mfma_f32_16x16x32_bf16 v[10:13], v[46:49], v[26:29], 0
	s_waitcnt lgkmcnt(7)
	v_mfma_f32_16x16x32_bf16 v[6:9], v[50:53], v[26:29], 0
	s_waitcnt lgkmcnt(6)
	v_mfma_f32_16x16x32_bf16 v[2:5], v[54:57], v[26:29], 0
	s_waitcnt vmcnt(0)
	v_mfma_f32_16x16x32_bf16 v[14:17], v[176:179], v[30:33], v[14:17]
	v_mfma_f32_16x16x32_bf16 v[10:13], v[180:183], v[30:33], v[10:13]
	v_mfma_f32_16x16x32_bf16 v[6:9], v[184:187], v[30:33], v[6:9]
	v_mfma_f32_16x16x32_bf16 v[2:5], v[188:191], v[30:33], v[2:5]
	s_waitcnt lgkmcnt(0)
	v_mfma_f32_16x16x32_bf16 v[14:17], v[212:215], v[34:37], v[14:17]
	v_mfma_f32_16x16x32_bf16 v[10:13], v[216:219], v[34:37], v[10:13]
	v_mfma_f32_16x16x32_bf16 v[6:9], v[220:223], v[34:37], v[6:9]
	v_mfma_f32_16x16x32_bf16 v[2:5], v[224:227], v[34:37], v[2:5]
	v_mfma_f32_16x16x32_bf16 v[14:17], v[192:195], v[38:41], v[14:17]
	v_mfma_f32_16x16x32_bf16 v[10:13], v[196:199], v[38:41], v[10:13]
	v_mfma_f32_16x16x32_bf16 v[6:9], v[200:203], v[38:41], v[6:9]
	v_mfma_f32_16x16x32_bf16 v[2:5], v[204:207], v[38:41], v[2:5]
	s_nop 7
	s_nop 1
	v_mul_f32_e32 v18, v15, v15
	v_mul_f32_e32 v19, v17, v17
	v_fmac_f32_e32 v18, v14, v14
	v_fmac_f32_e32 v19, v16, v16
	v_add_f32_e32 v18, v18, v19
	v_mul_f32_e32 v19, v11, v11
	v_mul_f32_e32 v20, v13, v13
	v_fmac_f32_e32 v19, v10, v10
	v_fmac_f32_e32 v20, v12, v12
	v_add_f32_e32 v19, v19, v20
	v_add_f32_e32 v18, v18, v19
	v_mul_f32_e32 v19, v7, v7
	v_mul_f32_e32 v20, v9, v9
	v_fmac_f32_e32 v19, v6, v6
	v_fmac_f32_e32 v20, v8, v8
	v_add_f32_e32 v19, v19, v20
	v_add_f32_e32 v18, v18, v19
	v_mul_f32_e32 v19, v3, v3
	v_mul_f32_e32 v20, v5, v5
	v_fmac_f32_e32 v19, v2, v2
	v_fmac_f32_e32 v20, v4, v4
	v_add_f32_e32 v19, v19, v20
	v_add_f32_e32 v18, v18, v19
	ds_bpermute_b32 v19, v124, v18
	s_waitcnt lgkmcnt(0)
	v_add_f32_e32 v18, v18, v19
	ds_bpermute_b32 v19, v125, v18
	s_and_saveexec_b64 s[38:39], s[12:13]
	s_cbranch_execz .LBB0_309
	s_waitcnt lgkmcnt(0)
	v_add_f32_e32 v18, v18, v19
	ds_write_b32 v142, v18
	s_branch .LBB0_309

; #define LAS __attribute__((address_space(3)))
; __device__ __forceinline__ unsigned cvt_pk_bf16(float lo, float hi) { const f32x2 v = {lo, hi}; const bf16x2_t r = __builtin_convertvector(v, bf16x2_t); return __builtin_bit_cast(unsigned, r); }
; __device__ __forceinline__ f32x4 ld_bf4(const bf16_t* p) { const u32x2 w = *(const u32x2*)p; return (f32x4){bflo(w.x), bfhi(w.x), bflo(w.y), bfhi(w.y)}; }
; __device__ __forceinline__ f32x4 shifted4(const bf16_t* Ut, bool has_prev, int c, const float* mu) {
;     const f32x4 u = ld_bf4(Ut + c); f32x4 p = ld_bf4((has_prev ? Ut - 1792 : Ut) + c); const float pm = has_prev ? 1.0f : 0.0f; p = p * pm;
;     const f32x4 m = *(const f32x4*)(mu + c); return u + m * (p - u);
; __device__ __forceinline__ void rwkv_prep_tile(LAS unsigned char* lds, const PrepArgs& P, int tt, int tid) {
;     ...
;         for (int e = 0; e < 8; ++e) { const int idx = tid + 512 * e, i = idx >> 6, c = (idx & 63) * 8; const bf16_t* Ut = P.U + (size_t)(t0 + i) * 1792; const bool hp = s0 + i > 0;
;             const f32x4 x0 = shifted4(Ut, hp, 1024 + c, P.mu), x1 = shifted4(Ut, hp, 1024 + c + 4, P.mu);
;             u32x4 o; o.x = cvt_pk_bf16(x0[0], x0[1]); o.y = cvt_pk_bf16(x0[2], x0[3]); o.z = cvt_pk_bf16(x1[0], x1[1]); o.w = cvt_pk_bf16(x1[2], x1[3]);
;             *(LAS u32x4*)(LAv + i * SV + c * 2) = o; }
.LBB0_407:
	v_mov_b64_e32 v[14:15], s[12:13]
	v_mov_b32_e32 v11, v10
	v_ashrrev_i32_e32 v13, 6, v11
	v_add_u32_e32 v16, s22, v13
	v_cmp_lt_i32_e32 vcc, s23, v13
	v_mad_i64_i32 v[18:19], s[8:9], v16, s80, v[14:15]
	s_nop 0
	v_cndmask_b32_e64 v23, 0, -1, vcc
	v_cndmask_b32_e32 v22, 0, v242, vcc
	v_cndmask_b32_e64 v176, 0, 1.0, vcc
	v_lshl_add_u64 v[20:21], v[18:19], 0, v[0:1]
	v_lshl_add_u64 v[32:33], v[18:19], 0, v[22:23]
	global_load_dwordx4 v[112:115], v[20:21], off offset:2048
	v_lshl_add_u64 v[32:33], v[32:33], 0, v[0:1]
	global_load_dwordx4 v[116:119], v[32:33], off offset:2048
	v_mad_u64_u32 v[192:193], s[8:9], v13, s7, v[12:13]
	v_add_u32_e32 v11, 0x200, v10
	v_ashrrev_i32_e32 v13, 6, v11
	v_add_u32_e32 v16, s22, v13
	v_cmp_lt_i32_e32 vcc, s23, v13
	v_mad_i64_i32 v[18:19], s[8:9], v16, s80, v[14:15]
	s_nop 0
	v_cndmask_b32_e64 v23, 0, -1, vcc
	v_cndmask_b32_e32 v22, 0, v242, vcc
	v_cndmask_b32_e64 v178, 0, 1.0, vcc
	v_lshl_add_u64 v[20:21], v[18:19], 0, v[0:1]
	v_lshl_add_u64 v[32:33], v[18:19], 0, v[22:23]
	global_load_dwordx4 v[120:123], v[20:21], off offset:2048
	v_lshl_add_u64 v[32:33], v[32:33], 0, v[0:1]
	global_load_dwordx4 v[124:127], v[32:33], off offset:2048
	v_mad_u64_u32 v[194:195], s[8:9], v13, s7, v[12:13]
	v_add_u32_e32 v11, 0x400, v10
	v_ashrrev_i32_e32 v13, 6, v11
	v_add_u32_e32 v16, s22, v13
	v_cmp_lt_i32_e32 vcc, s23, v13
	v_mad_i64_i32 v[18:19], s[8:9], v16, s80, v[14:15]
	s_nop 0
	v_cndmask_b32_e64 v23, 0, -1, vcc
	v_cndmask_b32_e32 v22, 0, v242, vcc
	v_cndmask_b32_e64 v180, 0, 1.0, vcc
	v_lshl_add_u64 v[20:21], v[18:19], 0, v[0:1]
	v_lshl_add_u64 v[32:33], v[18:19], 0, v[22:23]
	global_load_dwordx4 v[128:131], v[20:21], off offset:2048
	v_lshl_add_u64 v[32:33], v[32:33], 0, v[0:1]
	global_load_dwordx4 v[132:135], v[32:33], off offset:2048
	v_mad_u64_u32 v[196:197], s[8:9], v13, s7, v[12:13]
	v_add_u32_e32 v11, 0x600, v10
	v_ashrrev_i32_e32 v13, 6, v11
	v_add_u32_e32 v16, s22, v13
	v_cmp_lt_i32_e32 vcc, s23, v13
	v_mad_i64_i32 v[18:19], s[8:9], v16, s80, v[14:15]
	s_nop 0
	v_cndmask_b32_e64 v23, 0, -1, vcc
	v_cndmask_b32_e32 v22, 0, v242, vcc
	v_cndmask_b32_e64 v182, 0, 1.0, vcc
	v_lshl_add_u64 v[20:21], v[18:19], 0, v[0:1]
	v_lshl_add_u64 v[32:33], v[18:19], 0, v[22:23]
	global_load_dwordx4 v[136:139], v[20:21], off offset:2048
	v_lshl_add_u64 v[32:33], v[32:33], 0, v[0:1]
	global_load_dwordx4 v[140:143], v[32:33], off offset:2048
	v_mad_u64_u32 v[198:199], s[8:9], v13, s7, v[12:13]
	v_add_u32_e32 v11, 0x800, v10
	v_ashrrev_i32_e32 v13, 6, v11
	v_add_u32_e32 v16, s22, v13
	v_cmp_lt_i32_e32 vcc, s23, v13
	v_mad_i64_i32 v[18:19], s[8:9], v16, s80, v[14:15]
	s_nop 0
	v_cndmask_b32_e64 v23, 0, -1, vcc
	v_cndmask_b32_e32 v22, 0, v242, vcc
	v_cndmask_b32_e64 v184, 0, 1.0, vcc
	v_lshl_add_u64 v[20:21], v[18:19], 0, v[0:1]
	v_lshl_add_u64 v[32:33], v[18:19], 0, v[22:23]
	global_load_dwordx4 v[144:147], v[20:21], off offset:2048
	v_lshl_add_u64 v[32:33], v[32:33], 0, v[0:1]
	global_load_dwordx4 v[148:151], v[32:33], off offset:2048
	v_mad_u64_u32 v[200:201], s[8:9], v13, s7, v[12:13]
	v_add_u32_e32 v11, 0xa00, v10
	v_ashrrev_i32_e32 v13, 6, v11
	v_add_u32_e32 v16, s22, v13
	v_cmp_lt_i32_e32 vcc, s23, v13
	v_mad_i64_i32 v[18:19], s[8:9], v16, s80, v[14:15]
	s_nop 0
	v_cndmask_b32_e64 v23, 0, -1, vcc
	v_cndmask_b32_e32 v22, 0, v242, vcc
	v_cndmask_b32_e64 v186, 0, 1.0, vcc
	v_lshl_add_u64 v[20:21], v[18:19], 0, v[0:1]
	v_lshl_add_u64 v[32:33], v[18:19], 0, v[22:23]
	global_load_dwordx4 v[152:155], v[20:21], off offset:2048
	v_lshl_add_u64 v[32:33], v[32:33], 0, v[0:1]
	global_load_dwordx4 v[156:159], v[32:33], off offset:2048
	v_mad_u64_u32 v[202:203], s[8:9], v13, s7, v[12:13]
	v_add_u32_e32 v11, 0xc00, v10
	v_ashrrev_i32_e32 v13, 6, v11
	v_add_u32_e32 v16, s22, v13
	v_cmp_lt_i32_e32 vcc, s23, v13
	v_mad_i64_i32 v[18:19], s[8:9], v16, s80, v[14:15]
	s_nop 0
	v_cndmask_b32_e64 v23, 0, -1, vcc
	v_cndmask_b32_e32 v22, 0, v242, vcc
	v_cndmask_b32_e64 v188, 0, 1.0, vcc
	v_lshl_add_u64 v[20:21], v[18:19], 0, v[0:1]
	v_lshl_add_u64 v[32:33], v[18:19], 0, v[22:23]
	global_load_dwordx4 v[160:163], v[20:21], off offset:2048
	v_lshl_add_u64 v[32:33], v[32:33], 0, v[0:1]
	global_load_dwordx4 v[164:167], v[32:33], off offset:2048
	v_mad_u64_u32 v[204:205], s[8:9], v13, s7, v[12:13]
	v_add_u32_e32 v11, 0xe00, v10
	v_ashrrev_i32_e32 v13, 6, v11
	v_add_u32_e32 v16, s22, v13
	v_cmp_lt_i32_e32 vcc, s23, v13
	v_mad_i64_i32 v[18:19], s[8:9], v16, s80, v[14:15]
	s_nop 0
	v_cndmask_b32_e64 v23, 0, -1, vcc
	v_cndmask_b32_e32 v22, 0, v242, vcc
	v_cndmask_b32_e64 v190, 0, 1.0, vcc
	v_lshl_add_u64 v[20:21], v[18:19], 0, v[0:1]
	v_lshl_add_u64 v[32:33], v[18:19], 0, v[22:23]
	global_load_dwordx4 v[168:171], v[20:21], off offset:2048
	v_lshl_add_u64 v[32:33], v[32:33], 0, v[0:1]
	global_load_dwordx4 v[172:175], v[32:33], off offset:2048
	v_mad_u64_u32 v[206:207], s[8:9], v13, s7, v[12:13]
	s_waitcnt vmcnt(14)
; #define LAS __attribute__((address_space(3)))
; __device__ __forceinline__ unsigned cvt_pk_bf16(float lo, float hi) { const f32x2 v = {lo, hi}; const bf16x2_t r = __builtin_convertvector(v, bf16x2_t); return __builtin_bit_cast(unsigned, r); }
; __device__ __forceinline__ void rwkv_prep_tile(LAS unsigned char* lds, const PrepArgs& P, int tt, int tid) {
;     ...
;         for (int e = 0; e < 8; ++e) { const int idx = tid + 512 * e, i = idx >> 6, c = (idx & 63) * 8; const bf16_t* Ut = P.U + (size_t)(t0 + i) * 1792; const bool hp = s0 + i > 0;
;             const f32x4 x0 = shifted4(Ut, hp, 1024 + c, P.mu), x1 = shifted4(Ut, hp, 1024 + c + 4, P.mu);
;             u32x4 o; o.x = cvt_pk_bf16(x0[0], x0[1]); o.y = cvt_pk_bf16(x0[2], x0[3]); o.z = cvt_pk_bf16(x1[0], x1[1]); o.w = cvt_pk_bf16(x1[2], x1[3]);
;             *(LAS u32x4*)(LAv + i * SV + c * 2) = o; }
	v_lshlrev_b32_e32 v24, 16, v112
	v_and_b32_e32 v25, 0xffff0000, v112
	v_lshlrev_b32_e32 v112, 16, v113
	v_and_b32_e32 v113, 0xffff0000, v113
	v_lshlrev_b32_e32 v26, 16, v116
	v_and_b32_e32 v27, 0xffff0000, v116
	v_xor_b32_e32 v31, 0x80000000, v25
	v_xor_b32_e32 v30, 0x80000000, v24
	v_lshlrev_b32_e32 v116, 16, v117
	v_and_b32_e32 v117, 0xffff0000, v117
	v_pk_fma_f32 v[26:27], v[176:177], v[26:27], v[30:31] op_sel_hi:[0,1,1]
	v_xor_b32_e32 v31, 0x80000000, v113
	v_xor_b32_e32 v30, 0x80000000, v112
	v_pk_fma_f32 v[116:117], v[176:177], v[116:117], v[30:31] op_sel_hi:[0,1,1]
	v_pk_fma_f32 v[116:117], v[8:9], v[116:117], v[112:113]
	v_pk_fma_f32 v[112:113], v[6:7], v[26:27], v[24:25]
	v_lshlrev_b32_e32 v24, 16, v114
	v_and_b32_e32 v25, 0xffff0000, v114
	v_lshlrev_b32_e32 v114, 16, v115
	v_and_b32_e32 v115, 0xffff0000, v115
	v_lshlrev_b32_e32 v26, 16, v118
	v_and_b32_e32 v27, 0xffff0000, v118
	v_xor_b32_e32 v31, 0x80000000, v25
	v_xor_b32_e32 v30, 0x80000000, v24
	v_lshlrev_b32_e32 v118, 16, v119
	v_and_b32_e32 v119, 0xffff0000, v119
	v_pk_fma_f32 v[26:27], v[176:177], v[26:27], v[30:31] op_sel_hi:[0,1,1]
	v_xor_b32_e32 v31, 0x80000000, v115
	v_xor_b32_e32 v30, 0x80000000, v114
	v_pk_fma_f32 v[118:119], v[176:177], v[118:119], v[30:31] op_sel_hi:[0,1,1]
	v_pk_fma_f32 v[118:119], v[4:5], v[118:119], v[114:115]
	v_pk_fma_f32 v[114:115], v[2:3], v[26:27], v[24:25]
	v_cvt_pk_bf16_f32 v112, v112, v113
	v_cvt_pk_bf16_f32 v113, v116, v117
	v_cvt_pk_bf16_f32 v114, v114, v115
	v_cvt_pk_bf16_f32 v115, v118, v119
	ds_write_b128 v192, v[112:115] offset:35840
	s_waitcnt vmcnt(12)
	v_lshlrev_b32_e32 v24, 16, v120
	v_and_b32_e32 v25, 0xffff0000, v120
	v_lshlrev_b32_e32 v120, 16, v121
	v_and_b32_e32 v121, 0xffff0000, v121
	v_lshlrev_b32_e32 v26, 16, v124
	v_and_b32_e32 v27, 0xffff0000, v124
	v_xor_b32_e32 v31, 0x80000000, v25
	v_xor_b32_e32 v30, 0x80000000, v24
	v_lshlrev_b32_e32 v124, 16, v125
	v_and_b32_e32 v125, 0xffff0000, v125
	v_pk_fma_f32 v[26:27], v[178:179], v[26:27], v[30:31] op_sel_hi:[0,1,1]
	v_xor_b32_e32 v31, 0x80000000, v121
	v_xor_b32_e32 v30, 0x80000000, v120
	v_pk_fma_f32 v[124:125], v[178:179], v[124:125], v[30:31] op_sel_hi:[0,1,1]
	v_pk_fma_f32 v[124:125], v[8:9], v[124:125], v[120:121]
	v_pk_fma_f32 v[120:121], v[6:7], v[26:27], v[24:25]
	v_lshlrev_b32_e32 v24, 16, v122
	v_and_b32_e32 v25, 0xffff0000, v122
	v_lshlrev_b32_e32 v122, 16, v123
	v_and_b32_e32 v123, 0xffff0000, v123
	v_lshlrev_b32_e32 v26, 16, v126
	v_and_b32_e32 v27, 0xffff0000, v126
	v_xor_b32_e32 v31, 0x80000000, v25
	v_xor_b32_e32 v30, 0x80000000, v24
	v_lshlrev_b32_e32 v126, 16, v127
	v_and_b32_e32 v127, 0xffff0000, v127
	v_pk_fma_f32 v[26:27], v[178:179], v[26:27], v[30:31] op_sel_hi:[0,1,1]
	v_xor_b32_e32 v31, 0x80000000, v123
	v_xor_b32_e32 v30, 0x80000000, v122
	v_pk_fma_f32 v[126:127], v[178:179], v[126:127], v[30:31] op_sel_hi:[0,1,1]
	v_pk_fma_f32 v[126:127], v[4:5], v[126:127], v[122:123]
	v_pk_fma_f32 v[122:123], v[2:3], v[26:27], v[24:25]
	v_cvt_pk_bf16_f32 v120, v120, v121
	v_cvt_pk_bf16_f32 v121, v124, v125
	v_cvt_pk_bf16_f32 v122, v122, v123
	v_cvt_pk_bf16_f32 v123, v126, v127
	ds_write_b128 v194, v[120:123] offset:35840
	s_waitcnt vmcnt(10)
	v_lshlrev_b32_e32 v24, 16, v128
	v_and_b32_e32 v25, 0xffff0000, v128
	v_lshlrev_b32_e32 v128, 16, v129
	v_and_b32_e32 v129, 0xffff0000, v129
	v_lshlrev_b32_e32 v26, 16, v132
	v_and_b32_e32 v27, 0xffff0000, v132
	v_xor_b32_e32 v31, 0x80000000, v25
	v_xor_b32_e32 v30, 0x80000000, v24
	v_lshlrev_b32_e32 v132, 16, v133
	v_and_b32_e32 v133, 0xffff0000, v133
	v_pk_fma_f32 v[26:27], v[180:181], v[26:27], v[30:31] op_sel_hi:[0,1,1]
	v_xor_b32_e32 v31, 0x80000000, v129
	v_xor_b32_e32 v30, 0x80000000, v128
	v_pk_fma_f32 v[132:133], v[180:181], v[132:133], v[30:31] op_sel_hi:[0,1,1]
	v_pk_fma_f32 v[132:133], v[8:9], v[132:133], v[128:129]
	v_pk_fma_f32 v[128:129], v[6:7], v[26:27], v[24:25]
	v_lshlrev_b32_e32 v24, 16, v130
	v_and_b32_e32 v25, 0xffff0000, v130
	v_lshlrev_b32_e32 v130, 16, v131
	v_and_b32_e32 v131, 0xffff0000, v131
	v_lshlrev_b32_e32 v26, 16, v134
	v_and_b32_e32 v27, 0xffff0000, v134
	v_xor_b32_e32 v31, 0x80000000, v25
	v_xor_b32_e32 v30, 0x80000000, v24
	v_lshlrev_b32_e32 v134, 16, v135
	v_and_b32_e32 v135, 0xffff0000, v135
	v_pk_fma_f32 v[26:27], v[180:181], v[26:27], v[30:31] op_sel_hi:[0,1,1]
	v_xor_b32_e32 v31, 0x80000000, v131
	v_xor_b32_e32 v30, 0x80000000, v130
	v_pk_fma_f32 v[134:135], v[180:181], v[134:135], v[30:31] op_sel_hi:[0,1,1]
	v_pk_fma_f32 v[134:135], v[4:5], v[134:135], v[130:131]
	v_pk_fma_f32 v[130:131], v[2:3], v[26:27], v[24:25]
	v_cvt_pk_bf16_f32 v128, v128, v129
	v_cvt_pk_bf16_f32 v129, v132, v133
	v_cvt_pk_bf16_f32 v130, v130, v131
	v_cvt_pk_bf16_f32 v131, v134, v135
	ds_write_b128 v196, v[128:131] offset:35840
	s_waitcnt vmcnt(8)
	v_lshlrev_b32_e32 v24, 16, v136
	v_and_b32_e32 v25, 0xffff0000, v136
	v_lshlrev_b32_e32 v136, 16, v137
	v_and_b32_e32 v137, 0xffff0000, v137
	v_lshlrev_b32_e32 v26, 16, v140
	v_and_b32_e32 v27, 0xffff0000, v140
	v_xor_b32_e32 v31, 0x80000000, v25
	v_xor_b32_e32 v30, 0x80000000, v24
	v_lshlrev_b32_e32 v140, 16, v141
	v_and_b32_e32 v141, 0xffff0000, v141
	v_pk_fma_f32 v[26:27], v[182:183], v[26:27], v[30:31] op_sel_hi:[0,1,1]
	v_xor_b32_e32 v31, 0x80000000, v137
	v_xor_b32_e32 v30, 0x80000000, v136
	v_pk_fma_f32 v[140:141], v[182:183], v[140:141], v[30:31] op_sel_hi:[0,1,1]
	v_pk_fma_f32 v[140:141], v[8:9], v[140:141], v[136:137]
	v_pk_fma_f32 v[136:137], v[6:7], v[26:27], v[24:25]
	v_lshlrev_b32_e32 v24, 16, v138
	v_and_b32_e32 v25, 0xffff0000, v138
	v_lshlrev_b32_e32 v138, 16, v139
	v_and_b32_e32 v139, 0xffff0000, v139
	v_lshlrev_b32_e32 v26, 16, v142
	v_and_b32_e32 v27, 0xffff0000, v142
	v_xor_b32_e32 v31, 0x80000000, v25
	v_xor_b32_e32 v30, 0x80000000, v24
	v_lshlrev_b32_e32 v142, 16, v143
	v_and_b32_e32 v143, 0xffff0000, v143
	v_pk_fma_f32 v[26:27], v[182:183], v[26:27], v[30:31] op_sel_hi:[0,1,1]
	v_xor_b32_e32 v31, 0x80000000, v139
	v_xor_b32_e32 v30, 0x80000000, v138
	v_pk_fma_f32 v[142:143], v[182:183], v[142:143], v[30:31] op_sel_hi:[0,1,1]
	v_pk_fma_f32 v[142:143], v[4:5], v[142:143], v[138:139]
	v_pk_fma_f32 v[138:139], v[2:3], v[26:27], v[24:25]
	v_cvt_pk_bf16_f32 v136, v136, v137
	v_cvt_pk_bf16_f32 v137, v140, v141
	v_cvt_pk_bf16_f32 v138, v138, v139
	v_cvt_pk_bf16_f32 v139, v142, v143
	ds_write_b128 v198, v[136:139] offset:35840
	s_waitcnt vmcnt(6)
; #define LAS __attribute__((address_space(3)))
; __device__ __forceinline__ unsigned cvt_pk_bf16(float lo, float hi) { const f32x2 v = {lo, hi}; const bf16x2_t r = __builtin_convertvector(v, bf16x2_t); return __builtin_bit_cast(unsigned, r); }
; __device__ __forceinline__ void rwkv_prep_tile(LAS unsigned char* lds, const PrepArgs& P, int tt, int tid) {
;     ...
;         for (int e = 0; e < 8; ++e) { const int idx = tid + 512 * e, i = idx >> 6, c = (idx & 63) * 8; const bf16_t* Ut = P.U + (size_t)(t0 + i) * 1792; const bool hp = s0 + i > 0;
;             const f32x4 x0 = shifted4(Ut, hp, 1024 + c, P.mu), x1 = shifted4(Ut, hp, 1024 + c + 4, P.mu);
;             u32x4 o; o.x = cvt_pk_bf16(x0[0], x0[1]); o.y = cvt_pk_bf16(x0[2], x0[3]); o.z = cvt_pk_bf16(x1[0], x1[1]); o.w = cvt_pk_bf16(x1[2], x1[3]);
;             *(LAS u32x4*)(LAv + i * SV + c * 2) = o; }
	v_lshlrev_b32_e32 v24, 16, v144
	v_and_b32_e32 v25, 0xffff0000, v144
	v_lshlrev_b32_e32 v144, 16, v145
	v_and_b32_e32 v145, 0xffff0000, v145
	v_lshlrev_b32_e32 v26, 16, v148
	v_and_b32_e32 v27, 0xffff0000, v148
	v_xor_b32_e32 v31, 0x80000000, v25
	v_xor_b32_e32 v30, 0x80000000, v24
	v_lshlrev_b32_e32 v148, 16, v149
	v_and_b32_e32 v149, 0xffff0000, v149
	v_pk_fma_f32 v[26:27], v[184:185], v[26:27], v[30:31] op_sel_hi:[0,1,1]
	v_xor_b32_e32 v31, 0x80000000, v145
	v_xor_b32_e32 v30, 0x80000000, v144
	v_pk_fma_f32 v[148:149], v[184:185], v[148:149], v[30:31] op_sel_hi:[0,1,1]
	v_pk_fma_f32 v[148:149], v[8:9], v[148:149], v[144:145]
	v_pk_fma_f32 v[144:145], v[6:7], v[26:27], v[24:25]
	v_lshlrev_b32_e32 v24, 16, v146
	v_and_b32_e32 v25, 0xffff0000, v146
	v_lshlrev_b32_e32 v146, 16, v147
	v_and_b32_e32 v147, 0xffff0000, v147
	v_lshlrev_b32_e32 v26, 16, v150
	v_and_b32_e32 v27, 0xffff0000, v150
	v_xor_b32_e32 v31, 0x80000000, v25
	v_xor_b32_e32 v30, 0x80000000, v24
	v_lshlrev_b32_e32 v150, 16, v151
	v_and_b32_e32 v151, 0xffff0000, v151
	v_pk_fma_f32 v[26:27], v[184:185], v[26:27], v[30:31] op_sel_hi:[0,1,1]
	v_xor_b32_e32 v31, 0x80000000, v147
	v_xor_b32_e32 v30, 0x80000000, v146
	v_pk_fma_f32 v[150:151], v[184:185], v[150:151], v[30:31] op_sel_hi:[0,1,1]
	v_pk_fma_f32 v[150:151], v[4:5], v[150:151], v[146:147]
	v_pk_fma_f32 v[146:147], v[2:3], v[26:27], v[24:25]
	v_cvt_pk_bf16_f32 v144, v144, v145
	v_cvt_pk_bf16_f32 v145, v148, v149
	v_cvt_pk_bf16_f32 v146, v146, v147
	v_cvt_pk_bf16_f32 v147, v150, v151
	ds_write_b128 v200, v[144:147] offset:35840
	s_waitcnt vmcnt(4)
	v_lshlrev_b32_e32 v24, 16, v152
	v_and_b32_e32 v25, 0xffff0000, v152
	v_lshlrev_b32_e32 v152, 16, v153
	v_and_b32_e32 v153, 0xffff0000, v153
	v_lshlrev_b32_e32 v26, 16, v156
	v_and_b32_e32 v27, 0xffff0000, v156
	v_xor_b32_e32 v31, 0x80000000, v25
	v_xor_b32_e32 v30, 0x80000000, v24
	v_lshlrev_b32_e32 v156, 16, v157
	v_and_b32_e32 v157, 0xffff0000, v157
	v_pk_fma_f32 v[26:27], v[186:187], v[26:27], v[30:31] op_sel_hi:[0,1,1]
	v_xor_b32_e32 v31, 0x80000000, v153
	v_xor_b32_e32 v30, 0x80000000, v152
	v_pk_fma_f32 v[156:157], v[186:187], v[156:157], v[30:31] op_sel_hi:[0,1,1]
	v_pk_fma_f32 v[156:157], v[8:9], v[156:157], v[152:153]
	v_pk_fma_f32 v[152:153], v[6:7], v[26:27], v[24:25]
	v_lshlrev_b32_e32 v24, 16, v154
	v_and_b32_e32 v25, 0xffff0000, v154
	v_lshlrev_b32_e32 v154, 16, v155
	v_and_b32_e32 v155, 0xffff0000, v155
	v_lshlrev_b32_e32 v26, 16, v158
	v_and_b32_e32 v27, 0xffff0000, v158
	v_xor_b32_e32 v31, 0x80000000, v25
	v_xor_b32_e32 v30, 0x80000000, v24
	v_lshlrev_b32_e32 v158, 16, v159
	v_and_b32_e32 v159, 0xffff0000, v159
	v_pk_fma_f32 v[26:27], v[186:187], v[26:27], v[30:31] op_sel_hi:[0,1,1]
	v_xor_b32_e32 v31, 0x80000000, v155
	v_xor_b32_e32 v30, 0x80000000, v154
	v_pk_fma_f32 v[158:159], v[186:187], v[158:159], v[30:31] op_sel_hi:[0,1,1]
	v_pk_fma_f32 v[158:159], v[4:5], v[158:159], v[154:155]
	v_pk_fma_f32 v[154:155], v[2:3], v[26:27], v[24:25]
	v_cvt_pk_bf16_f32 v152, v152, v153
	v_cvt_pk_bf16_f32 v153, v156, v157
	v_cvt_pk_bf16_f32 v154, v154, v155
	v_cvt_pk_bf16_f32 v155, v158, v159
	ds_write_b128 v202, v[152:155] offset:35840
	s_waitcnt vmcnt(2)
	v_lshlrev_b32_e32 v24, 16, v160
	v_and_b32_e32 v25, 0xffff0000, v160
	v_lshlrev_b32_e32 v160, 16, v161
	v_and_b32_e32 v161, 0xffff0000, v161
	v_lshlrev_b32_e32 v26, 16, v164
	v_and_b32_e32 v27, 0xffff0000, v164
	v_xor_b32_e32 v31, 0x80000000, v25
	v_xor_b32_e32 v30, 0x80000000, v24
	v_lshlrev_b32_e32 v164, 16, v165
	v_and_b32_e32 v165, 0xffff0000, v165
	v_pk_fma_f32 v[26:27], v[188:189], v[26:27], v[30:31] op_sel_hi:[0,1,1]
	v_xor_b32_e32 v31, 0x80000000, v161
	v_xor_b32_e32 v30, 0x80000000, v160
	v_pk_fma_f32 v[164:165], v[188:189], v[164:165], v[30:31] op_sel_hi:[0,1,1]
	v_pk_fma_f32 v[164:165], v[8:9], v[164:165], v[160:161]
	v_pk_fma_f32 v[160:161], v[6:7], v[26:27], v[24:25]
	v_lshlrev_b32_e32 v24, 16, v162
	v_and_b32_e32 v25, 0xffff0000, v162
	v_lshlrev_b32_e32 v162, 16, v163
	v_and_b32_e32 v163, 0xffff0000, v163
	v_lshlrev_b32_e32 v26, 16, v166
	v_and_b32_e32 v27, 0xffff0000, v166
	v_xor_b32_e32 v31, 0x80000000, v25
	v_xor_b32_e32 v30, 0x80000000, v24
	v_lshlrev_b32_e32 v166, 16, v167
	v_and_b32_e32 v167, 0xffff0000, v167
	v_pk_fma_f32 v[26:27], v[188:189], v[26:27], v[30:31] op_sel_hi:[0,1,1]
	v_xor_b32_e32 v31, 0x80000000, v163
	v_xor_b32_e32 v30, 0x80000000, v162
	v_pk_fma_f32 v[166:167], v[188:189], v[166:167], v[30:31] op_sel_hi:[0,1,1]
	v_pk_fma_f32 v[166:167], v[4:5], v[166:167], v[162:163]
	v_pk_fma_f32 v[162:163], v[2:3], v[26:27], v[24:25]
	v_cvt_pk_bf16_f32 v160, v160, v161
	v_cvt_pk_bf16_f32 v161, v164, v165
	v_cvt_pk_bf16_f32 v162, v162, v163
	v_cvt_pk_bf16_f32 v163, v166, v167
	ds_write_b128 v204, v[160:163] offset:35840
	s_waitcnt vmcnt(0)
	v_lshlrev_b32_e32 v24, 16, v168
	v_and_b32_e32 v25, 0xffff0000, v168
	v_lshlrev_b32_e32 v168, 16, v169
	v_and_b32_e32 v169, 0xffff0000, v169
	v_lshlrev_b32_e32 v26, 16, v172
	v_and_b32_e32 v27, 0xffff0000, v172
	v_xor_b32_e32 v31, 0x80000000, v25
	v_xor_b32_e32 v30, 0x80000000, v24
	v_lshlrev_b32_e32 v172, 16, v173
	v_and_b32_e32 v173, 0xffff0000, v173
	v_pk_fma_f32 v[26:27], v[190:191], v[26:27], v[30:31] op_sel_hi:[0,1,1]
	v_xor_b32_e32 v31, 0x80000000, v169
	v_xor_b32_e32 v30, 0x80000000, v168
	v_pk_fma_f32 v[172:173], v[190:191], v[172:173], v[30:31] op_sel_hi:[0,1,1]
	v_pk_fma_f32 v[172:173], v[8:9], v[172:173], v[168:169]
	v_pk_fma_f32 v[168:169], v[6:7], v[26:27], v[24:25]
	v_lshlrev_b32_e32 v24, 16, v170
	v_and_b32_e32 v25, 0xffff0000, v170
	v_lshlrev_b32_e32 v170, 16, v171
	v_and_b32_e32 v171, 0xffff0000, v171
	v_lshlrev_b32_e32 v26, 16, v174
	v_and_b32_e32 v27, 0xffff0000, v174
	v_xor_b32_e32 v31, 0x80000000, v25
	v_xor_b32_e32 v30, 0x80000000, v24
	v_lshlrev_b32_e32 v174, 16, v175
	v_and_b32_e32 v175, 0xffff0000, v175
	v_pk_fma_f32 v[26:27], v[190:191], v[26:27], v[30:31] op_sel_hi:[0,1,1]
	v_xor_b32_e32 v31, 0x80000000, v171
	v_xor_b32_e32 v30, 0x80000000, v170
	v_pk_fma_f32 v[174:175], v[190:191], v[174:175], v[30:31] op_sel_hi:[0,1,1]
	v_pk_fma_f32 v[174:175], v[4:5], v[174:175], v[170:171]
	v_pk_fma_f32 v[170:171], v[2:3], v[26:27], v[24:25]
	v_cvt_pk_bf16_f32 v168, v168, v169
	v_cvt_pk_bf16_f32 v169, v172, v173
	v_cvt_pk_bf16_f32 v170, v170, v171
	v_cvt_pk_bf16_f32 v171, v174, v175
	ds_write_b128 v206, v[168:171] offset:35840
	s_movk_i32 s58, 0x410

; #define LAS __attribute__((address_space(3)))
; __device__ __forceinline__ unsigned cvt_pk_bf16(float lo, float hi) { const f32x2 v = {lo, hi}; const bf16x2_t r = __builtin_convertvector(v, bf16x2_t); return __builtin_bit_cast(unsigned, r); }
; __device__ __forceinline__ f32x4 mfma16(bf16x8 a, bf16x8 b, f32x4 c) { return __builtin_amdgcn_mfma_f32_16x16x32_bf16(a, b, c, 0, 0, 0); }
; __device__ __forceinline__ void rwkv_prep_tile(LAS unsigned char* lds, const PrepArgs& P, int tt, int tid) {
;     ...
;         const int mt = wave >> 1, nt = wave & 1; f32x4 acc = (f32x4){0.f, 0.f, 0.f, 0.f};
; #pragma unroll 4
;         for (int ks = 0; ks < 16; ++ks) { const bf16x8 a = *(LAS const bf16x8*)(LAv + (16 * mt + fr) * SV + (ks * 32 + fq * 8) * 2);
;             const bf16x8 b = *(const bf16x8*)(P.v1t + (size_t)(16 * nt + fr) * 512 + ks * 32 + fq * 8); acc = mfma16(b, a, acc); }
;         u32x2 w; w.x = cvt_pk_bf16(acc[0], acc[1]); w.y = cvt_pk_bf16(acc[2], acc[3]); *(LAS u32x2*)(LAvv + (16 * mt + fr) * SVV + (16 * nt + 4 * fq) * 2) = w;
.LBB0_411:
	global_load_dwordx4 v[112:115], v[6:7], off offset:-128
	global_load_dwordx4 v[116:119], v[6:7], off offset:-64
	global_load_dwordx4 v[120:123], v[6:7], off
	global_load_dwordx4 v[124:127], v[6:7], off offset:64
	global_load_dwordx4 v[128:131], v[6:7], off offset:128
	global_load_dwordx4 v[132:135], v[6:7], off offset:192
	global_load_dwordx4 v[136:139], v[6:7], off offset:256
	global_load_dwordx4 v[140:143], v[6:7], off offset:320
	global_load_dwordx4 v[144:147], v[6:7], off offset:384
	global_load_dwordx4 v[148:151], v[6:7], off offset:448
	global_load_dwordx4 v[152:155], v[6:7], off offset:512
	global_load_dwordx4 v[156:159], v[6:7], off offset:576
	global_load_dwordx4 v[160:163], v[6:7], off offset:640
	global_load_dwordx4 v[164:167], v[6:7], off offset:704
	global_load_dwordx4 v[168:171], v[6:7], off offset:768
	global_load_dwordx4 v[172:175], v[6:7], off offset:832
	ds_read_b128 v[176:179], v11
	ds_read_b128 v[180:183], v11 offset:64
	ds_read_b128 v[184:187], v11 offset:128
	ds_read_b128 v[188:191], v11 offset:192
	ds_read_b128 v[192:195], v11 offset:256
	ds_read_b128 v[196:199], v11 offset:320
	ds_read_b128 v[200:203], v11 offset:384
	ds_read_b128 v[204:207], v11 offset:448
	s_waitcnt vmcnt(15) lgkmcnt(7)
	v_mfma_f32_16x16x32_bf16 v[2:5], v[112:115], v[176:179], v[2:5]
	s_waitcnt vmcnt(14) lgkmcnt(6)
	v_mfma_f32_16x16x32_bf16 v[2:5], v[116:119], v[180:183], v[2:5]
	s_waitcnt vmcnt(13) lgkmcnt(5)
	v_mfma_f32_16x16x32_bf16 v[2:5], v[120:123], v[184:187], v[2:5]
	s_waitcnt vmcnt(12) lgkmcnt(4)
	v_mfma_f32_16x16x32_bf16 v[2:5], v[124:127], v[188:191], v[2:5]
	s_waitcnt vmcnt(11) lgkmcnt(3)
	v_mfma_f32_16x16x32_bf16 v[2:5], v[128:131], v[192:195], v[2:5]
	s_waitcnt vmcnt(10) lgkmcnt(2)
	v_mfma_f32_16x16x32_bf16 v[2:5], v[132:135], v[196:199], v[2:5]
	s_waitcnt vmcnt(9) lgkmcnt(1)
	v_mfma_f32_16x16x32_bf16 v[2:5], v[136:139], v[200:203], v[2:5]
	s_waitcnt vmcnt(8) lgkmcnt(0)
	v_mfma_f32_16x16x32_bf16 v[2:5], v[140:143], v[204:207], v[2:5]
	ds_read_b128 v[12:15], v11 offset:512
	ds_read_b128 v[16:19], v11 offset:576
	ds_read_b128 v[20:23], v11 offset:640
	ds_read_b128 v[24:27], v11 offset:704
	ds_read_b128 v[28:31], v11 offset:768
	ds_read_b128 v[32:35], v11 offset:832
	ds_read_b128 v[36:39], v11 offset:896
	ds_read_b128 v[40:43], v11 offset:960
	s_waitcnt vmcnt(7) lgkmcnt(7)
	v_mfma_f32_16x16x32_bf16 v[2:5], v[144:147], v[12:15], v[2:5]
	s_waitcnt vmcnt(6) lgkmcnt(6)
	v_mfma_f32_16x16x32_bf16 v[2:5], v[148:151], v[16:19], v[2:5]
	s_waitcnt vmcnt(5) lgkmcnt(5)
	v_mfma_f32_16x16x32_bf16 v[2:5], v[152:155], v[20:23], v[2:5]
	s_waitcnt vmcnt(4) lgkmcnt(4)
	v_mfma_f32_16x16x32_bf16 v[2:5], v[156:159], v[24:27], v[2:5]
	s_waitcnt vmcnt(3) lgkmcnt(3)
	v_mfma_f32_16x16x32_bf16 v[2:5], v[160:163], v[28:31], v[2:5]
	s_waitcnt vmcnt(2) lgkmcnt(2)
	v_mfma_f32_16x16x32_bf16 v[2:5], v[164:167], v[32:35], v[2:5]
	s_waitcnt vmcnt(1) lgkmcnt(1)
	v_mfma_f32_16x16x32_bf16 v[2:5], v[168:171], v[36:39], v[2:5]
	s_waitcnt vmcnt(0) lgkmcnt(0)
	v_mfma_f32_16x16x32_bf16 v[2:5], v[172:175], v[40:43], v[2:5]
	s_nop 1
	s_and_b32 s7, s7, 0xffffff0
	s_lshl_b32 s6, s6, 5
	v_or_b32_e32 v6, s7, v106
	s_movk_i32 s7, 0x50
	s_add_i32 s6, s6, 0
	v_lshlrev_b32_e32 v0, 3, v8
	s_nop 0
	v_cvt_pk_bf16_f32 v2, v2, v3
	v_cvt_pk_bf16_f32 v3, v4, v5
	v_mul_lo_u32 v4, v6, s7
	s_add_i32 s6, s6, 0x19000
	v_add3_u32 v4, s6, v4, v0
	ds_write_b64 v4, v[2:3]
	s_mov_b64 s[6:7], 0
	v_mov_b64_e32 v[2:3], v[0:1]
